# v8 + B-only responsibility-split L2 prefetch addressed from the loop's own b2 pointer (K-steps t+2,t+3, next-unit aware at the unit boundary), 8 lanes per wave per iteration
# speedup vs baseline: 1.0204x; 1.0043x over previous
.LBB0_340:
	s_and_b32 s99, s54, 7
	s_lshl_b32 s99, s99, 5
	v_and_b32_e32 v244, 7, v0
	v_lshrrev_b32_e32 v245, 6, v0
	v_lshl_add_u32 v244, v245, 3, v244
	v_and_b32_e32 v245, 31, v244
	v_add_u32_e32 v245, s99, v245
	v_lshrrev_b32_e32 v246, 5, v244
	v_lshlrev_b32_e32 v245, 13, v245
	v_lshl_add_u32 v250, v246, 7, v245
	v_mov_b32_e32 v251, 0
	v_add_u32_e32 v252, 0x10000, v159
	s_add_u32 s12, s12, 0x100080
	s_addc_u32 s13, s13, 0
	s_add_u32 s0, s14, 0x100
	v_mov_b32_e32 v2, 0
	s_addc_u32 s1, s15, 0
	s_mov_b32 s39, -2
	v_mov_b32_e32 v3, v2
	v_mov_b32_e32 v4, v2
	v_mov_b32_e32 v5, v2
	v_mov_b32_e32 v6, v2
	v_mov_b32_e32 v7, v2
	v_mov_b32_e32 v8, v2
	v_mov_b32_e32 v9, v2
	v_mov_b32_e32 v18, v2
	v_mov_b32_e32 v19, v2
	v_mov_b32_e32 v20, v2
	v_mov_b32_e32 v21, v2
	v_mov_b32_e32 v22, v2
	v_mov_b32_e32 v23, v2
	v_mov_b32_e32 v24, v2
	v_mov_b32_e32 v25, v2
	v_mov_b32_e32 v34, v2
	v_mov_b32_e32 v35, v2
	v_mov_b32_e32 v36, v2
	v_mov_b32_e32 v37, v2
	v_mov_b32_e32 v38, v2
	v_mov_b32_e32 v39, v2
	v_mov_b32_e32 v40, v2
	v_mov_b32_e32 v41, v2
	v_mov_b32_e32 v50, v2
	v_mov_b32_e32 v51, v2
	v_mov_b32_e32 v52, v2
	v_mov_b32_e32 v53, v2
	v_mov_b32_e32 v54, v2
	v_mov_b32_e32 v55, v2
	v_mov_b32_e32 v56, v2
	v_mov_b32_e32 v57, v2
	v_mov_b32_e32 v10, v2
	v_mov_b32_e32 v11, v2
	v_mov_b32_e32 v12, v2
	v_mov_b32_e32 v13, v2
	v_mov_b32_e32 v14, v2
	v_mov_b32_e32 v15, v2
	v_mov_b32_e32 v16, v2
	v_mov_b32_e32 v17, v2
	v_mov_b32_e32 v26, v2
	v_mov_b32_e32 v27, v2
	v_mov_b32_e32 v28, v2
	v_mov_b32_e32 v29, v2
	v_mov_b32_e32 v30, v2
	v_mov_b32_e32 v31, v2
	v_mov_b32_e32 v32, v2
	v_mov_b32_e32 v33, v2
	v_mov_b32_e32 v42, v2
	v_mov_b32_e32 v43, v2
	v_mov_b32_e32 v44, v2
	v_mov_b32_e32 v45, v2
	v_mov_b32_e32 v46, v2
	v_mov_b32_e32 v47, v2
	v_mov_b32_e32 v48, v2
	v_mov_b32_e32 v49, v2
	v_mov_b32_e32 v58, v2
	v_mov_b32_e32 v59, v2
	v_mov_b32_e32 v60, v2
	v_mov_b32_e32 v61, v2
	v_mov_b32_e32 v62, v2
	v_mov_b32_e32 v63, v2
	v_mov_b32_e32 v64, v2
	v_mov_b32_e32 v65, v2
	v_mov_b32_e32 v66, v2
	v_mov_b32_e32 v67, v2
	v_mov_b32_e32 v68, v2
	v_mov_b32_e32 v69, v2
	v_mov_b32_e32 v70, v2
	v_mov_b32_e32 v71, v2
	v_mov_b32_e32 v72, v2
	v_mov_b32_e32 v73, v2
	v_mov_b32_e32 v82, v2
	v_mov_b32_e32 v83, v2
	v_mov_b32_e32 v84, v2
	v_mov_b32_e32 v85, v2
	v_mov_b32_e32 v86, v2
	v_mov_b32_e32 v87, v2
	v_mov_b32_e32 v88, v2
	v_mov_b32_e32 v89, v2
	v_mov_b32_e32 v98, v2
	v_mov_b32_e32 v99, v2
	v_mov_b32_e32 v100, v2
	v_mov_b32_e32 v101, v2
	v_mov_b32_e32 v102, v2
	v_mov_b32_e32 v103, v2
	v_mov_b32_e32 v104, v2
	v_mov_b32_e32 v105, v2
	v_mov_b32_e32 v114, v2
	v_mov_b32_e32 v115, v2
	v_mov_b32_e32 v116, v2
	v_mov_b32_e32 v117, v2
	v_mov_b32_e32 v118, v2
	v_mov_b32_e32 v119, v2
	v_mov_b32_e32 v120, v2
	v_mov_b32_e32 v121, v2
	v_mov_b32_e32 v74, v2
	v_mov_b32_e32 v75, v2
	v_mov_b32_e32 v76, v2
	v_mov_b32_e32 v77, v2
	v_mov_b32_e32 v78, v2
	v_mov_b32_e32 v79, v2
	v_mov_b32_e32 v80, v2
	v_mov_b32_e32 v81, v2
	v_mov_b32_e32 v90, v2
	v_mov_b32_e32 v91, v2
	v_mov_b32_e32 v92, v2
	v_mov_b32_e32 v93, v2
	v_mov_b32_e32 v94, v2
	v_mov_b32_e32 v95, v2
	v_mov_b32_e32 v96, v2
	v_mov_b32_e32 v97, v2
	v_mov_b32_e32 v106, v2
	v_mov_b32_e32 v107, v2
	v_mov_b32_e32 v108, v2
	v_mov_b32_e32 v109, v2
	v_mov_b32_e32 v110, v2
	v_mov_b32_e32 v111, v2
	v_mov_b32_e32 v112, v2
	v_mov_b32_e32 v113, v2
	v_mov_b32_e32 v122, v2
	v_mov_b32_e32 v123, v2
	v_mov_b32_e32 v124, v2
	v_mov_b32_e32 v125, v2
	v_mov_b32_e32 v126, v2
	v_mov_b32_e32 v127, v2
	v_mov_b32_e32 v128, v2
	v_mov_b32_e32 v129, v2
.LBB0_341:
	s_add_u32 s14, s12, 0xfff00080
	s_addc_u32 s15, s13, -1
	s_cmp_eq_u32 s39, 60
	s_cselect_b32 s17, s51, s15
	s_cselect_b32 s16, s50, s14
	s_cselect_b32 s15, s53, s1
	s_cselect_b32 s14, s52, s0
	v_lshl_add_u64 v[242:243], s[14:15], 0, v[250:251]
	s_add_i32 m0, s8, 0xc000
	ds_read_b128 v[152:155], v252
	ds_read_b128 v[162:165], v252 offset:1024
	global_load_lds_dwordx4 v148, s[12:13]
	s_add_i32 m0, s8, 0xe000
	ds_read_b128 v[166:169], v252 offset:2048
	ds_read_b128 v[170:173], v252 offset:3072
	global_load_lds_dwordx4 v150, s[12:13]
	ds_read_b128 v[174:177], v252 offset:16384
	ds_read_b128 v[182:185], v252 offset:17408
	ds_read_b128 v[186:189], v252 offset:18432
	ds_read_b128 v[190:193], v252 offset:19456
	ds_read_b128 v[194:197], v161
	ds_read_b128 v[198:201], v161 offset:1024
	ds_read_b128 v[202:205], v161 offset:2048
	ds_read_b128 v[206:209], v161 offset:3072
	ds_read_b128 v[210:213], v161 offset:4096
	ds_read_b128 v[214:217], v161 offset:5120
	ds_read_b128 v[218:221], v161 offset:6144
	ds_read_b128 v[222:225], v161 offset:7168
	s_waitcnt vmcnt(8)
	s_mov_b32 m0, 0x21800
	s_mov_b64 exec, 0xff
	s_waitcnt lgkmcnt(0)
	global_load_lds_dword v[242:243], off
	s_mov_b64 exec, -1
	s_barrier
	v_mfma_f32_16x16x32_bf16 v[126:129], v[152:155], v[194:197], v[126:129]
	v_mfma_f32_16x16x32_bf16 v[126:129], v[162:165], v[198:201], v[126:129]
	v_mfma_f32_16x16x32_bf16 v[122:125], v[166:169], v[194:197], v[122:125]
	v_mfma_f32_16x16x32_bf16 v[122:125], v[170:173], v[198:201], v[122:125]
	v_mfma_f32_16x16x32_bf16 v[110:113], v[152:155], v[202:205], v[110:113]
	v_mfma_f32_16x16x32_bf16 v[110:113], v[162:165], v[206:209], v[110:113]
	v_mfma_f32_16x16x32_bf16 v[106:109], v[166:169], v[202:205], v[106:109]
	v_mfma_f32_16x16x32_bf16 v[106:109], v[170:173], v[206:209], v[106:109]
	v_mfma_f32_16x16x32_bf16 v[94:97], v[152:155], v[210:213], v[94:97]
	v_mfma_f32_16x16x32_bf16 v[94:97], v[162:165], v[214:217], v[94:97]
	v_mfma_f32_16x16x32_bf16 v[90:93], v[166:169], v[210:213], v[90:93]
	v_mfma_f32_16x16x32_bf16 v[90:93], v[170:173], v[214:217], v[90:93]
	v_mfma_f32_16x16x32_bf16 v[78:81], v[152:155], v[218:221], v[78:81]
	v_mfma_f32_16x16x32_bf16 v[78:81], v[162:165], v[222:225], v[78:81]
	v_mfma_f32_16x16x32_bf16 v[74:77], v[166:169], v[218:221], v[74:77]
	v_mfma_f32_16x16x32_bf16 v[74:77], v[170:173], v[222:225], v[74:77]
	v_mfma_f32_16x16x32_bf16 v[118:121], v[174:177], v[194:197], v[118:121]
	v_mfma_f32_16x16x32_bf16 v[118:121], v[182:185], v[198:201], v[118:121]
	v_mfma_f32_16x16x32_bf16 v[114:117], v[186:189], v[194:197], v[114:117]
	v_mfma_f32_16x16x32_bf16 v[114:117], v[190:193], v[198:201], v[114:117]
	v_mfma_f32_16x16x32_bf16 v[102:105], v[174:177], v[202:205], v[102:105]
	v_mfma_f32_16x16x32_bf16 v[102:105], v[182:185], v[206:209], v[102:105]
	v_mfma_f32_16x16x32_bf16 v[98:101], v[186:189], v[202:205], v[98:101]
	v_mfma_f32_16x16x32_bf16 v[98:101], v[190:193], v[206:209], v[98:101]
	v_mfma_f32_16x16x32_bf16 v[86:89], v[174:177], v[210:213], v[86:89]
	v_mfma_f32_16x16x32_bf16 v[86:89], v[182:185], v[214:217], v[86:89]
	v_mfma_f32_16x16x32_bf16 v[82:85], v[186:189], v[210:213], v[82:85]
	v_mfma_f32_16x16x32_bf16 v[82:85], v[190:193], v[214:217], v[82:85]
	v_mfma_f32_16x16x32_bf16 v[70:73], v[174:177], v[218:221], v[70:73]
	v_mfma_f32_16x16x32_bf16 v[70:73], v[182:185], v[222:225], v[70:73]
	v_mfma_f32_16x16x32_bf16 v[66:69], v[186:189], v[218:221], v[66:69]
	v_mfma_f32_16x16x32_bf16 v[66:69], v[190:193], v[222:225], v[66:69]
	s_barrier
	s_add_i32 m0, s28, 0x10000
	ds_read_b128 v[194:197], v161 offset:16384
	ds_read_b128 v[198:201], v161 offset:17408
	global_load_lds_dwordx4 v144, s[14:15]
	s_add_i32 m0, s28, 0x12000
	s_add_u32 s98, s14, 0x100000
	s_addc_u32 s99, s15, 0
	ds_read_b128 v[202:205], v161 offset:18432
	global_load_lds_dwordx4 v140, s[14:15]
	s_add_i32 m0, s28, 0x14000
	ds_read_b128 v[206:209], v161 offset:19456
	ds_read_b128 v[210:213], v161 offset:20480
	global_load_lds_dwordx4 v144, s[98:99]
	s_add_i32 m0, s28, 0x16000
	ds_read_b128 v[214:217], v161 offset:21504
	ds_read_b128 v[218:221], v161 offset:22528
	global_load_lds_dwordx4 v140, s[98:99]
	s_mov_b32 m0, s8
	ds_read_b128 v[222:225], v161 offset:23552
	global_load_lds_dwordx4 v146, s[16:17]
	s_mov_b32 m0, s9
	s_nop 0
	global_load_lds_dwordx4 v142, s[16:17]
	s_waitcnt vmcnt(9)
	s_waitcnt lgkmcnt(0)
	s_barrier
	v_mfma_f32_16x16x32_bf16 v[62:65], v[152:155], v[194:197], v[62:65]
	v_mfma_f32_16x16x32_bf16 v[62:65], v[162:165], v[198:201], v[62:65]
	v_mfma_f32_16x16x32_bf16 v[58:61], v[166:169], v[194:197], v[58:61]
	v_mfma_f32_16x16x32_bf16 v[58:61], v[170:173], v[198:201], v[58:61]
	v_mfma_f32_16x16x32_bf16 v[46:49], v[152:155], v[202:205], v[46:49]
	v_mfma_f32_16x16x32_bf16 v[46:49], v[162:165], v[206:209], v[46:49]
	v_mfma_f32_16x16x32_bf16 v[42:45], v[166:169], v[202:205], v[42:45]
	v_mfma_f32_16x16x32_bf16 v[42:45], v[170:173], v[206:209], v[42:45]
	v_mfma_f32_16x16x32_bf16 v[30:33], v[152:155], v[210:213], v[30:33]
	v_mfma_f32_16x16x32_bf16 v[30:33], v[162:165], v[214:217], v[30:33]
	v_mfma_f32_16x16x32_bf16 v[26:29], v[166:169], v[210:213], v[26:29]
	v_mfma_f32_16x16x32_bf16 v[26:29], v[170:173], v[214:217], v[26:29]
	v_mfma_f32_16x16x32_bf16 v[14:17], v[152:155], v[218:221], v[14:17]
	v_mfma_f32_16x16x32_bf16 v[14:17], v[162:165], v[222:225], v[14:17]
	v_mfma_f32_16x16x32_bf16 v[10:13], v[166:169], v[218:221], v[10:13]
	v_mfma_f32_16x16x32_bf16 v[10:13], v[170:173], v[222:225], v[10:13]
	v_mfma_f32_16x16x32_bf16 v[54:57], v[174:177], v[194:197], v[54:57]
	v_mfma_f32_16x16x32_bf16 v[54:57], v[182:185], v[198:201], v[54:57]
	v_mfma_f32_16x16x32_bf16 v[50:53], v[186:189], v[194:197], v[50:53]
	v_mfma_f32_16x16x32_bf16 v[50:53], v[190:193], v[198:201], v[50:53]
	v_mfma_f32_16x16x32_bf16 v[38:41], v[174:177], v[202:205], v[38:41]
	v_mfma_f32_16x16x32_bf16 v[38:41], v[182:185], v[206:209], v[38:41]
	v_mfma_f32_16x16x32_bf16 v[34:37], v[186:189], v[202:205], v[34:37]
	v_mfma_f32_16x16x32_bf16 v[34:37], v[190:193], v[206:209], v[34:37]
	v_mfma_f32_16x16x32_bf16 v[22:25], v[174:177], v[210:213], v[22:25]
	v_mfma_f32_16x16x32_bf16 v[22:25], v[182:185], v[214:217], v[22:25]
	v_mfma_f32_16x16x32_bf16 v[18:21], v[186:189], v[210:213], v[18:21]
	v_mfma_f32_16x16x32_bf16 v[18:21], v[190:193], v[214:217], v[18:21]
	v_mfma_f32_16x16x32_bf16 v[6:9], v[174:177], v[218:221], v[6:9]
	v_mfma_f32_16x16x32_bf16 v[6:9], v[182:185], v[222:225], v[6:9]
	v_mfma_f32_16x16x32_bf16 v[2:5], v[186:189], v[218:221], v[2:5]
	v_mfma_f32_16x16x32_bf16 v[2:5], v[190:193], v[222:225], v[2:5]
	s_barrier
	s_add_u32 s100, s16, 0x100000
	s_addc_u32 s101, s17, 0
	s_mov_b32 m0, s29
	ds_read_b128 v[152:155], v252 offset:32768
	ds_read_b128 v[162:165], v252 offset:33792
	global_load_lds_dwordx4 v146, s[100:101]
	s_mov_b32 m0, s36
	ds_read_b128 v[166:169], v252 offset:34816
	ds_read_b128 v[170:173], v252 offset:35840
	global_load_lds_dwordx4 v142, s[100:101]
	ds_read_b128 v[174:177], v252 offset:49152
	ds_read_b128 v[182:185], v252 offset:50176
	ds_read_b128 v[186:189], v252 offset:51200
	ds_read_b128 v[190:193], v252 offset:52224
	ds_read_b128 v[194:197], v161 offset:32768
	ds_read_b128 v[198:201], v161 offset:33792
	ds_read_b128 v[202:205], v161 offset:34816
	ds_read_b128 v[206:209], v161 offset:35840
	ds_read_b128 v[210:213], v161 offset:36864
	ds_read_b128 v[214:217], v161 offset:37888
	ds_read_b128 v[218:221], v161 offset:38912
	ds_read_b128 v[222:225], v161 offset:39936
	s_waitcnt vmcnt(9)
	s_waitcnt lgkmcnt(0)
	s_barrier
	v_mfma_f32_16x16x32_bf16 v[126:129], v[152:155], v[194:197], v[126:129]
	v_mfma_f32_16x16x32_bf16 v[126:129], v[162:165], v[198:201], v[126:129]
	v_mfma_f32_16x16x32_bf16 v[122:125], v[166:169], v[194:197], v[122:125]
	v_mfma_f32_16x16x32_bf16 v[122:125], v[170:173], v[198:201], v[122:125]
	v_mfma_f32_16x16x32_bf16 v[110:113], v[152:155], v[202:205], v[110:113]
	v_mfma_f32_16x16x32_bf16 v[110:113], v[162:165], v[206:209], v[110:113]
	v_mfma_f32_16x16x32_bf16 v[106:109], v[166:169], v[202:205], v[106:109]
	v_mfma_f32_16x16x32_bf16 v[106:109], v[170:173], v[206:209], v[106:109]
	v_mfma_f32_16x16x32_bf16 v[94:97], v[152:155], v[210:213], v[94:97]
	v_mfma_f32_16x16x32_bf16 v[94:97], v[162:165], v[214:217], v[94:97]
	v_mfma_f32_16x16x32_bf16 v[90:93], v[166:169], v[210:213], v[90:93]
	v_mfma_f32_16x16x32_bf16 v[90:93], v[170:173], v[214:217], v[90:93]
	v_mfma_f32_16x16x32_bf16 v[78:81], v[152:155], v[218:221], v[78:81]
	v_mfma_f32_16x16x32_bf16 v[78:81], v[162:165], v[222:225], v[78:81]
	v_mfma_f32_16x16x32_bf16 v[74:77], v[166:169], v[218:221], v[74:77]
	v_mfma_f32_16x16x32_bf16 v[74:77], v[170:173], v[222:225], v[74:77]
	v_mfma_f32_16x16x32_bf16 v[118:121], v[174:177], v[194:197], v[118:121]
	v_mfma_f32_16x16x32_bf16 v[118:121], v[182:185], v[198:201], v[118:121]
	v_mfma_f32_16x16x32_bf16 v[114:117], v[186:189], v[194:197], v[114:117]
	v_mfma_f32_16x16x32_bf16 v[114:117], v[190:193], v[198:201], v[114:117]
	v_mfma_f32_16x16x32_bf16 v[102:105], v[174:177], v[202:205], v[102:105]
	v_mfma_f32_16x16x32_bf16 v[102:105], v[182:185], v[206:209], v[102:105]
	v_mfma_f32_16x16x32_bf16 v[98:101], v[186:189], v[202:205], v[98:101]
	v_mfma_f32_16x16x32_bf16 v[98:101], v[190:193], v[206:209], v[98:101]
	v_mfma_f32_16x16x32_bf16 v[86:89], v[174:177], v[210:213], v[86:89]
	v_mfma_f32_16x16x32_bf16 v[86:89], v[182:185], v[214:217], v[86:89]
	v_mfma_f32_16x16x32_bf16 v[82:85], v[186:189], v[210:213], v[82:85]
	v_mfma_f32_16x16x32_bf16 v[82:85], v[190:193], v[214:217], v[82:85]
	v_mfma_f32_16x16x32_bf16 v[70:73], v[174:177], v[218:221], v[70:73]
	v_mfma_f32_16x16x32_bf16 v[70:73], v[182:185], v[222:225], v[70:73]
	v_mfma_f32_16x16x32_bf16 v[66:69], v[186:189], v[218:221], v[66:69]
	v_mfma_f32_16x16x32_bf16 v[66:69], v[190:193], v[222:225], v[66:69]
	s_barrier
	s_add_u32 s14, s14, 0x80
	s_addc_u32 s15, s15, 0
	s_add_i32 m0, s28, 0x18000
	ds_read_b128 v[194:197], v161 offset:49152
	ds_read_b128 v[198:201], v161 offset:50176
	global_load_lds_dwordx4 v144, s[14:15]
	s_add_i32 m0, s28, 0x1a000
	s_add_u32 s98, s98, 0x80
	s_addc_u32 s99, s99, 0
	ds_read_b128 v[202:205], v161 offset:51200
	global_load_lds_dwordx4 v140, s[14:15]
	s_add_i32 m0, s28, 0x1c000
	ds_read_b128 v[206:209], v161 offset:52224
	ds_read_b128 v[210:213], v161 offset:53248
	global_load_lds_dwordx4 v144, s[98:99]
	s_add_i32 m0, s28, 0x1e000
	s_add_u32 s16, s16, 0x80
	s_addc_u32 s17, s17, 0
	ds_read_b128 v[214:217], v161 offset:54272
	ds_read_b128 v[218:221], v161 offset:55296
	global_load_lds_dwordx4 v140, s[98:99]
	s_mov_b32 m0, s45
	ds_read_b128 v[222:225], v161 offset:56320
	global_load_lds_dwordx4 v146, s[16:17]
	s_mov_b32 m0, s46
	s_nop 0
	global_load_lds_dwordx4 v142, s[16:17]
	s_waitcnt vmcnt(8)
	s_waitcnt lgkmcnt(0)
	s_barrier
	v_mfma_f32_16x16x32_bf16 v[62:65], v[152:155], v[194:197], v[62:65]
	v_mfma_f32_16x16x32_bf16 v[62:65], v[162:165], v[198:201], v[62:65]
	v_mfma_f32_16x16x32_bf16 v[58:61], v[166:169], v[194:197], v[58:61]
	v_mfma_f32_16x16x32_bf16 v[58:61], v[170:173], v[198:201], v[58:61]
	v_mfma_f32_16x16x32_bf16 v[46:49], v[152:155], v[202:205], v[46:49]
	v_mfma_f32_16x16x32_bf16 v[46:49], v[162:165], v[206:209], v[46:49]
	v_mfma_f32_16x16x32_bf16 v[42:45], v[166:169], v[202:205], v[42:45]
	v_mfma_f32_16x16x32_bf16 v[42:45], v[170:173], v[206:209], v[42:45]
	v_mfma_f32_16x16x32_bf16 v[30:33], v[152:155], v[210:213], v[30:33]
	v_mfma_f32_16x16x32_bf16 v[30:33], v[162:165], v[214:217], v[30:33]
	v_mfma_f32_16x16x32_bf16 v[26:29], v[166:169], v[210:213], v[26:29]
	v_mfma_f32_16x16x32_bf16 v[26:29], v[170:173], v[214:217], v[26:29]
	v_mfma_f32_16x16x32_bf16 v[14:17], v[152:155], v[218:221], v[14:17]
	v_mfma_f32_16x16x32_bf16 v[14:17], v[162:165], v[222:225], v[14:17]
	v_mfma_f32_16x16x32_bf16 v[10:13], v[166:169], v[218:221], v[10:13]
	v_mfma_f32_16x16x32_bf16 v[10:13], v[170:173], v[222:225], v[10:13]
	v_mfma_f32_16x16x32_bf16 v[54:57], v[174:177], v[194:197], v[54:57]
	v_mfma_f32_16x16x32_bf16 v[54:57], v[182:185], v[198:201], v[54:57]
	v_mfma_f32_16x16x32_bf16 v[50:53], v[186:189], v[194:197], v[50:53]
	v_mfma_f32_16x16x32_bf16 v[50:53], v[190:193], v[198:201], v[50:53]
	v_mfma_f32_16x16x32_bf16 v[38:41], v[174:177], v[202:205], v[38:41]
	v_mfma_f32_16x16x32_bf16 v[38:41], v[182:185], v[206:209], v[38:41]
	v_mfma_f32_16x16x32_bf16 v[34:37], v[186:189], v[202:205], v[34:37]
	v_mfma_f32_16x16x32_bf16 v[34:37], v[190:193], v[206:209], v[34:37]
	v_mfma_f32_16x16x32_bf16 v[22:25], v[174:177], v[210:213], v[22:25]
	v_mfma_f32_16x16x32_bf16 v[22:25], v[182:185], v[214:217], v[22:25]
	v_mfma_f32_16x16x32_bf16 v[18:21], v[186:189], v[210:213], v[18:21]
	v_mfma_f32_16x16x32_bf16 v[18:21], v[190:193], v[214:217], v[18:21]
	v_mfma_f32_16x16x32_bf16 v[6:9], v[174:177], v[218:221], v[6:9]
	v_mfma_f32_16x16x32_bf16 v[6:9], v[182:185], v[222:225], v[6:9]
	v_mfma_f32_16x16x32_bf16 v[2:5], v[186:189], v[218:221], v[2:5]
	v_mfma_f32_16x16x32_bf16 v[2:5], v[190:193], v[222:225], v[2:5]
	s_barrier
	s_add_i32 s39, s39, 2
	s_add_u32 s12, s12, 0x100
	s_addc_u32 s13, s13, 0
	s_add_u32 s0, s0, 0x100
	s_addc_u32 s1, s1, 0
	s_cmp_gt_u32 s39, 61
	s_cbranch_scc0 .LBB0_341
	s_and_b64 vcc, exec, s[34:35]
	s_cbranch_vccz .LBB0_344
	s_barrier

.LBB0_571:
	s_and_b32 s99, s46, 7
	s_lshl_b32 s99, s99, 5
	v_and_b32_e32 v244, 7, v0
	v_lshrrev_b32_e32 v245, 6, v0
	v_lshl_add_u32 v244, v245, 3, v244
	v_and_b32_e32 v245, 31, v244
	v_add_u32_e32 v245, s99, v245
	v_lshrrev_b32_e32 v246, 5, v244
	v_lshlrev_b32_e32 v245, 13, v245
	v_lshl_add_u32 v250, v246, 7, v245
	v_mov_b32_e32 v251, 0
	v_add_u32_e32 v252, 0x10000, v159
	s_add_u32 s12, s12, 0x100080
	s_addc_u32 s13, s13, 0
	s_add_u32 s0, s14, 0x100
	v_mov_b32_e32 v2, 0
	s_addc_u32 s1, s15, 0
	s_mov_b32 s35, -2
	v_mov_b32_e32 v3, v2
	v_mov_b32_e32 v4, v2
	v_mov_b32_e32 v5, v2
	v_mov_b32_e32 v6, v2
	v_mov_b32_e32 v7, v2
	v_mov_b32_e32 v8, v2
	v_mov_b32_e32 v9, v2
	v_mov_b32_e32 v18, v2
	v_mov_b32_e32 v19, v2
	v_mov_b32_e32 v20, v2
	v_mov_b32_e32 v21, v2
	v_mov_b32_e32 v22, v2
	v_mov_b32_e32 v23, v2
	v_mov_b32_e32 v24, v2
	v_mov_b32_e32 v25, v2
	v_mov_b32_e32 v34, v2
	v_mov_b32_e32 v35, v2
	v_mov_b32_e32 v36, v2
	v_mov_b32_e32 v37, v2
	v_mov_b32_e32 v38, v2
	v_mov_b32_e32 v39, v2
	v_mov_b32_e32 v40, v2
	v_mov_b32_e32 v41, v2
	v_mov_b32_e32 v50, v2
	v_mov_b32_e32 v51, v2
	v_mov_b32_e32 v52, v2
	v_mov_b32_e32 v53, v2
	v_mov_b32_e32 v54, v2
	v_mov_b32_e32 v55, v2
	v_mov_b32_e32 v56, v2
	v_mov_b32_e32 v57, v2
	v_mov_b32_e32 v10, v2
	v_mov_b32_e32 v11, v2
	v_mov_b32_e32 v12, v2
	v_mov_b32_e32 v13, v2
	v_mov_b32_e32 v14, v2
	v_mov_b32_e32 v15, v2
	v_mov_b32_e32 v16, v2
	v_mov_b32_e32 v17, v2
	v_mov_b32_e32 v26, v2
	v_mov_b32_e32 v27, v2
	v_mov_b32_e32 v28, v2
	v_mov_b32_e32 v29, v2
	v_mov_b32_e32 v30, v2
	v_mov_b32_e32 v31, v2
	v_mov_b32_e32 v32, v2
	v_mov_b32_e32 v33, v2
	v_mov_b32_e32 v42, v2
	v_mov_b32_e32 v43, v2
	v_mov_b32_e32 v44, v2
	v_mov_b32_e32 v45, v2
	v_mov_b32_e32 v46, v2
	v_mov_b32_e32 v47, v2
	v_mov_b32_e32 v48, v2
	v_mov_b32_e32 v49, v2
	v_mov_b32_e32 v58, v2
	v_mov_b32_e32 v59, v2
	v_mov_b32_e32 v60, v2
	v_mov_b32_e32 v61, v2
	v_mov_b32_e32 v62, v2
	v_mov_b32_e32 v63, v2
	v_mov_b32_e32 v64, v2
	v_mov_b32_e32 v65, v2
	v_mov_b32_e32 v66, v2
	v_mov_b32_e32 v67, v2
	v_mov_b32_e32 v68, v2
	v_mov_b32_e32 v69, v2
	v_mov_b32_e32 v70, v2
	v_mov_b32_e32 v71, v2
	v_mov_b32_e32 v72, v2
	v_mov_b32_e32 v73, v2
	v_mov_b32_e32 v82, v2
	v_mov_b32_e32 v83, v2
	v_mov_b32_e32 v84, v2
	v_mov_b32_e32 v85, v2
	v_mov_b32_e32 v86, v2
	v_mov_b32_e32 v87, v2
	v_mov_b32_e32 v88, v2
	v_mov_b32_e32 v89, v2
	v_mov_b32_e32 v98, v2
	v_mov_b32_e32 v99, v2
	v_mov_b32_e32 v100, v2
	v_mov_b32_e32 v101, v2
	v_mov_b32_e32 v102, v2
	v_mov_b32_e32 v103, v2
	v_mov_b32_e32 v104, v2
	v_mov_b32_e32 v105, v2
	v_mov_b32_e32 v114, v2
	v_mov_b32_e32 v115, v2
	v_mov_b32_e32 v116, v2
	v_mov_b32_e32 v117, v2
	v_mov_b32_e32 v118, v2
	v_mov_b32_e32 v119, v2
	v_mov_b32_e32 v120, v2
	v_mov_b32_e32 v121, v2
	v_mov_b32_e32 v74, v2
	v_mov_b32_e32 v75, v2
	v_mov_b32_e32 v76, v2
	v_mov_b32_e32 v77, v2
	v_mov_b32_e32 v78, v2
	v_mov_b32_e32 v79, v2
	v_mov_b32_e32 v80, v2
	v_mov_b32_e32 v81, v2
	v_mov_b32_e32 v90, v2
	v_mov_b32_e32 v91, v2
	v_mov_b32_e32 v92, v2
	v_mov_b32_e32 v93, v2
	v_mov_b32_e32 v94, v2
	v_mov_b32_e32 v95, v2
	v_mov_b32_e32 v96, v2
	v_mov_b32_e32 v97, v2
	v_mov_b32_e32 v106, v2
	v_mov_b32_e32 v107, v2
	v_mov_b32_e32 v108, v2
	v_mov_b32_e32 v109, v2
	v_mov_b32_e32 v110, v2
	v_mov_b32_e32 v111, v2
	v_mov_b32_e32 v112, v2
	v_mov_b32_e32 v113, v2
	v_mov_b32_e32 v122, v2
	v_mov_b32_e32 v123, v2
	v_mov_b32_e32 v124, v2
	v_mov_b32_e32 v125, v2
	v_mov_b32_e32 v126, v2
	v_mov_b32_e32 v127, v2
	v_mov_b32_e32 v128, v2
	v_mov_b32_e32 v129, v2
.LBB0_572:
	s_add_u32 s14, s12, 0xfff00080
	s_addc_u32 s15, s13, -1
	s_cmp_eq_u32 s35, 60
	s_cselect_b32 s17, s51, s15
	s_cselect_b32 s16, s50, s14
	s_cselect_b32 s15, s53, s1
	s_cselect_b32 s14, s52, s0
	v_lshl_add_u64 v[242:243], s[14:15], 0, v[250:251]
	s_add_i32 m0, s8, 0xc000
	ds_read_b128 v[152:155], v252
	ds_read_b128 v[162:165], v252 offset:1024
	global_load_lds_dwordx4 v148, s[12:13]
	s_add_i32 m0, s8, 0xe000
	ds_read_b128 v[166:169], v252 offset:2048
	ds_read_b128 v[170:173], v252 offset:3072
	global_load_lds_dwordx4 v150, s[12:13]
	ds_read_b128 v[174:177], v252 offset:16384
	ds_read_b128 v[182:185], v252 offset:17408
	ds_read_b128 v[186:189], v252 offset:18432
	ds_read_b128 v[190:193], v252 offset:19456
	ds_read_b128 v[194:197], v161
	ds_read_b128 v[198:201], v161 offset:1024
	ds_read_b128 v[202:205], v161 offset:2048
	ds_read_b128 v[206:209], v161 offset:3072
	ds_read_b128 v[210:213], v161 offset:4096
	ds_read_b128 v[214:217], v161 offset:5120
	ds_read_b128 v[218:221], v161 offset:6144
	ds_read_b128 v[222:225], v161 offset:7168
	s_waitcnt vmcnt(8)
	s_mov_b32 m0, 0x21800
	s_mov_b64 exec, 0xff
	s_waitcnt lgkmcnt(0)
	global_load_lds_dword v[242:243], off
	s_mov_b64 exec, -1
	s_barrier
	v_mfma_f32_16x16x32_bf16 v[126:129], v[152:155], v[194:197], v[126:129]
	v_mfma_f32_16x16x32_bf16 v[126:129], v[162:165], v[198:201], v[126:129]
	v_mfma_f32_16x16x32_bf16 v[122:125], v[166:169], v[194:197], v[122:125]
	v_mfma_f32_16x16x32_bf16 v[122:125], v[170:173], v[198:201], v[122:125]
	v_mfma_f32_16x16x32_bf16 v[110:113], v[152:155], v[202:205], v[110:113]
	v_mfma_f32_16x16x32_bf16 v[110:113], v[162:165], v[206:209], v[110:113]
	v_mfma_f32_16x16x32_bf16 v[106:109], v[166:169], v[202:205], v[106:109]
	v_mfma_f32_16x16x32_bf16 v[106:109], v[170:173], v[206:209], v[106:109]
	v_mfma_f32_16x16x32_bf16 v[94:97], v[152:155], v[210:213], v[94:97]
	v_mfma_f32_16x16x32_bf16 v[94:97], v[162:165], v[214:217], v[94:97]
	v_mfma_f32_16x16x32_bf16 v[90:93], v[166:169], v[210:213], v[90:93]
	v_mfma_f32_16x16x32_bf16 v[90:93], v[170:173], v[214:217], v[90:93]
	v_mfma_f32_16x16x32_bf16 v[78:81], v[152:155], v[218:221], v[78:81]
	v_mfma_f32_16x16x32_bf16 v[78:81], v[162:165], v[222:225], v[78:81]
	v_mfma_f32_16x16x32_bf16 v[74:77], v[166:169], v[218:221], v[74:77]
	v_mfma_f32_16x16x32_bf16 v[74:77], v[170:173], v[222:225], v[74:77]
	v_mfma_f32_16x16x32_bf16 v[118:121], v[174:177], v[194:197], v[118:121]
	v_mfma_f32_16x16x32_bf16 v[118:121], v[182:185], v[198:201], v[118:121]
	v_mfma_f32_16x16x32_bf16 v[114:117], v[186:189], v[194:197], v[114:117]
	v_mfma_f32_16x16x32_bf16 v[114:117], v[190:193], v[198:201], v[114:117]
	v_mfma_f32_16x16x32_bf16 v[102:105], v[174:177], v[202:205], v[102:105]
	v_mfma_f32_16x16x32_bf16 v[102:105], v[182:185], v[206:209], v[102:105]
	v_mfma_f32_16x16x32_bf16 v[98:101], v[186:189], v[202:205], v[98:101]
	v_mfma_f32_16x16x32_bf16 v[98:101], v[190:193], v[206:209], v[98:101]
	v_mfma_f32_16x16x32_bf16 v[86:89], v[174:177], v[210:213], v[86:89]
	v_mfma_f32_16x16x32_bf16 v[86:89], v[182:185], v[214:217], v[86:89]
	v_mfma_f32_16x16x32_bf16 v[82:85], v[186:189], v[210:213], v[82:85]
	v_mfma_f32_16x16x32_bf16 v[82:85], v[190:193], v[214:217], v[82:85]
	v_mfma_f32_16x16x32_bf16 v[70:73], v[174:177], v[218:221], v[70:73]
	v_mfma_f32_16x16x32_bf16 v[70:73], v[182:185], v[222:225], v[70:73]
	v_mfma_f32_16x16x32_bf16 v[66:69], v[186:189], v[218:221], v[66:69]
	v_mfma_f32_16x16x32_bf16 v[66:69], v[190:193], v[222:225], v[66:69]
	s_barrier
	s_add_i32 m0, s28, 0x10000
	ds_read_b128 v[194:197], v161 offset:16384
	ds_read_b128 v[198:201], v161 offset:17408
	global_load_lds_dwordx4 v144, s[14:15]
	s_add_i32 m0, s28, 0x12000
	s_add_u32 s98, s14, 0x100000
	s_addc_u32 s99, s15, 0
	ds_read_b128 v[202:205], v161 offset:18432
	global_load_lds_dwordx4 v140, s[14:15]
	s_add_i32 m0, s28, 0x14000
	ds_read_b128 v[206:209], v161 offset:19456
	ds_read_b128 v[210:213], v161 offset:20480
	global_load_lds_dwordx4 v144, s[98:99]
	s_add_i32 m0, s28, 0x16000
	ds_read_b128 v[214:217], v161 offset:21504
	ds_read_b128 v[218:221], v161 offset:22528
	global_load_lds_dwordx4 v140, s[98:99]
	s_mov_b32 m0, s8
	ds_read_b128 v[222:225], v161 offset:23552
	global_load_lds_dwordx4 v146, s[16:17]
	s_mov_b32 m0, s9
	s_nop 0
	global_load_lds_dwordx4 v142, s[16:17]
	s_waitcnt vmcnt(9)
	s_waitcnt lgkmcnt(0)
	s_barrier
	v_mfma_f32_16x16x32_bf16 v[62:65], v[152:155], v[194:197], v[62:65]
	v_mfma_f32_16x16x32_bf16 v[62:65], v[162:165], v[198:201], v[62:65]
	v_mfma_f32_16x16x32_bf16 v[58:61], v[166:169], v[194:197], v[58:61]
	v_mfma_f32_16x16x32_bf16 v[58:61], v[170:173], v[198:201], v[58:61]
	v_mfma_f32_16x16x32_bf16 v[46:49], v[152:155], v[202:205], v[46:49]
	v_mfma_f32_16x16x32_bf16 v[46:49], v[162:165], v[206:209], v[46:49]
	v_mfma_f32_16x16x32_bf16 v[42:45], v[166:169], v[202:205], v[42:45]
	v_mfma_f32_16x16x32_bf16 v[42:45], v[170:173], v[206:209], v[42:45]
	v_mfma_f32_16x16x32_bf16 v[30:33], v[152:155], v[210:213], v[30:33]
	v_mfma_f32_16x16x32_bf16 v[30:33], v[162:165], v[214:217], v[30:33]
	v_mfma_f32_16x16x32_bf16 v[26:29], v[166:169], v[210:213], v[26:29]
	v_mfma_f32_16x16x32_bf16 v[26:29], v[170:173], v[214:217], v[26:29]
	v_mfma_f32_16x16x32_bf16 v[14:17], v[152:155], v[218:221], v[14:17]
	v_mfma_f32_16x16x32_bf16 v[14:17], v[162:165], v[222:225], v[14:17]
	v_mfma_f32_16x16x32_bf16 v[10:13], v[166:169], v[218:221], v[10:13]
	v_mfma_f32_16x16x32_bf16 v[10:13], v[170:173], v[222:225], v[10:13]
	v_mfma_f32_16x16x32_bf16 v[54:57], v[174:177], v[194:197], v[54:57]
	v_mfma_f32_16x16x32_bf16 v[54:57], v[182:185], v[198:201], v[54:57]
	v_mfma_f32_16x16x32_bf16 v[50:53], v[186:189], v[194:197], v[50:53]
	v_mfma_f32_16x16x32_bf16 v[50:53], v[190:193], v[198:201], v[50:53]
	v_mfma_f32_16x16x32_bf16 v[38:41], v[174:177], v[202:205], v[38:41]
	v_mfma_f32_16x16x32_bf16 v[38:41], v[182:185], v[206:209], v[38:41]
	v_mfma_f32_16x16x32_bf16 v[34:37], v[186:189], v[202:205], v[34:37]
	v_mfma_f32_16x16x32_bf16 v[34:37], v[190:193], v[206:209], v[34:37]
	v_mfma_f32_16x16x32_bf16 v[22:25], v[174:177], v[210:213], v[22:25]
	v_mfma_f32_16x16x32_bf16 v[22:25], v[182:185], v[214:217], v[22:25]
	v_mfma_f32_16x16x32_bf16 v[18:21], v[186:189], v[210:213], v[18:21]
	v_mfma_f32_16x16x32_bf16 v[18:21], v[190:193], v[214:217], v[18:21]
	v_mfma_f32_16x16x32_bf16 v[6:9], v[174:177], v[218:221], v[6:9]
	v_mfma_f32_16x16x32_bf16 v[6:9], v[182:185], v[222:225], v[6:9]
	v_mfma_f32_16x16x32_bf16 v[2:5], v[186:189], v[218:221], v[2:5]
	v_mfma_f32_16x16x32_bf16 v[2:5], v[190:193], v[222:225], v[2:5]
	s_barrier
	s_add_u32 s100, s16, 0x100000
	s_addc_u32 s101, s17, 0
	s_mov_b32 m0, s29
	ds_read_b128 v[152:155], v252 offset:32768
	ds_read_b128 v[162:165], v252 offset:33792
	global_load_lds_dwordx4 v146, s[100:101]
	s_mov_b32 m0, s36
	ds_read_b128 v[166:169], v252 offset:34816
	ds_read_b128 v[170:173], v252 offset:35840
	global_load_lds_dwordx4 v142, s[100:101]
	ds_read_b128 v[174:177], v252 offset:49152
	ds_read_b128 v[182:185], v252 offset:50176
	ds_read_b128 v[186:189], v252 offset:51200
	ds_read_b128 v[190:193], v252 offset:52224
	ds_read_b128 v[194:197], v161 offset:32768
	ds_read_b128 v[198:201], v161 offset:33792
	ds_read_b128 v[202:205], v161 offset:34816
	ds_read_b128 v[206:209], v161 offset:35840
	ds_read_b128 v[210:213], v161 offset:36864
	ds_read_b128 v[214:217], v161 offset:37888
	ds_read_b128 v[218:221], v161 offset:38912
	ds_read_b128 v[222:225], v161 offset:39936
	s_waitcnt vmcnt(9)
	s_waitcnt lgkmcnt(0)
	s_barrier
	v_mfma_f32_16x16x32_bf16 v[126:129], v[152:155], v[194:197], v[126:129]
	v_mfma_f32_16x16x32_bf16 v[126:129], v[162:165], v[198:201], v[126:129]
	v_mfma_f32_16x16x32_bf16 v[122:125], v[166:169], v[194:197], v[122:125]
	v_mfma_f32_16x16x32_bf16 v[122:125], v[170:173], v[198:201], v[122:125]
	v_mfma_f32_16x16x32_bf16 v[110:113], v[152:155], v[202:205], v[110:113]
	v_mfma_f32_16x16x32_bf16 v[110:113], v[162:165], v[206:209], v[110:113]
	v_mfma_f32_16x16x32_bf16 v[106:109], v[166:169], v[202:205], v[106:109]
	v_mfma_f32_16x16x32_bf16 v[106:109], v[170:173], v[206:209], v[106:109]
	v_mfma_f32_16x16x32_bf16 v[94:97], v[152:155], v[210:213], v[94:97]
	v_mfma_f32_16x16x32_bf16 v[94:97], v[162:165], v[214:217], v[94:97]
	v_mfma_f32_16x16x32_bf16 v[90:93], v[166:169], v[210:213], v[90:93]
	v_mfma_f32_16x16x32_bf16 v[90:93], v[170:173], v[214:217], v[90:93]
	v_mfma_f32_16x16x32_bf16 v[78:81], v[152:155], v[218:221], v[78:81]
	v_mfma_f32_16x16x32_bf16 v[78:81], v[162:165], v[222:225], v[78:81]
	v_mfma_f32_16x16x32_bf16 v[74:77], v[166:169], v[218:221], v[74:77]
	v_mfma_f32_16x16x32_bf16 v[74:77], v[170:173], v[222:225], v[74:77]
	v_mfma_f32_16x16x32_bf16 v[118:121], v[174:177], v[194:197], v[118:121]
	v_mfma_f32_16x16x32_bf16 v[118:121], v[182:185], v[198:201], v[118:121]
	v_mfma_f32_16x16x32_bf16 v[114:117], v[186:189], v[194:197], v[114:117]
	v_mfma_f32_16x16x32_bf16 v[114:117], v[190:193], v[198:201], v[114:117]
	v_mfma_f32_16x16x32_bf16 v[102:105], v[174:177], v[202:205], v[102:105]
	v_mfma_f32_16x16x32_bf16 v[102:105], v[182:185], v[206:209], v[102:105]
	v_mfma_f32_16x16x32_bf16 v[98:101], v[186:189], v[202:205], v[98:101]
	v_mfma_f32_16x16x32_bf16 v[98:101], v[190:193], v[206:209], v[98:101]
	v_mfma_f32_16x16x32_bf16 v[86:89], v[174:177], v[210:213], v[86:89]
	v_mfma_f32_16x16x32_bf16 v[86:89], v[182:185], v[214:217], v[86:89]
	v_mfma_f32_16x16x32_bf16 v[82:85], v[186:189], v[210:213], v[82:85]
	v_mfma_f32_16x16x32_bf16 v[82:85], v[190:193], v[214:217], v[82:85]
	v_mfma_f32_16x16x32_bf16 v[70:73], v[174:177], v[218:221], v[70:73]
	v_mfma_f32_16x16x32_bf16 v[70:73], v[182:185], v[222:225], v[70:73]
	v_mfma_f32_16x16x32_bf16 v[66:69], v[186:189], v[218:221], v[66:69]
	v_mfma_f32_16x16x32_bf16 v[66:69], v[190:193], v[222:225], v[66:69]
	s_barrier
	s_add_u32 s14, s14, 0x80
	s_addc_u32 s15, s15, 0
	s_add_i32 m0, s28, 0x18000
	ds_read_b128 v[194:197], v161 offset:49152
	ds_read_b128 v[198:201], v161 offset:50176
	global_load_lds_dwordx4 v144, s[14:15]
	s_add_i32 m0, s28, 0x1a000
	s_add_u32 s98, s98, 0x80
	s_addc_u32 s99, s99, 0
	ds_read_b128 v[202:205], v161 offset:51200
	global_load_lds_dwordx4 v140, s[14:15]
	s_add_i32 m0, s28, 0x1c000
	ds_read_b128 v[206:209], v161 offset:52224
	ds_read_b128 v[210:213], v161 offset:53248
	global_load_lds_dwordx4 v144, s[98:99]
	s_add_i32 m0, s28, 0x1e000
	s_add_u32 s16, s16, 0x80
	s_addc_u32 s17, s17, 0
	ds_read_b128 v[214:217], v161 offset:54272
	ds_read_b128 v[218:221], v161 offset:55296
	global_load_lds_dwordx4 v140, s[98:99]
	s_mov_b32 m0, s39
	ds_read_b128 v[222:225], v161 offset:56320
	global_load_lds_dwordx4 v146, s[16:17]
	s_mov_b32 m0, s44
	s_nop 0
	global_load_lds_dwordx4 v142, s[16:17]
	s_waitcnt vmcnt(8)
	s_waitcnt lgkmcnt(0)
	s_barrier
	v_mfma_f32_16x16x32_bf16 v[62:65], v[152:155], v[194:197], v[62:65]
	v_mfma_f32_16x16x32_bf16 v[62:65], v[162:165], v[198:201], v[62:65]
	v_mfma_f32_16x16x32_bf16 v[58:61], v[166:169], v[194:197], v[58:61]
	v_mfma_f32_16x16x32_bf16 v[58:61], v[170:173], v[198:201], v[58:61]
	v_mfma_f32_16x16x32_bf16 v[46:49], v[152:155], v[202:205], v[46:49]
	v_mfma_f32_16x16x32_bf16 v[46:49], v[162:165], v[206:209], v[46:49]
	v_mfma_f32_16x16x32_bf16 v[42:45], v[166:169], v[202:205], v[42:45]
	v_mfma_f32_16x16x32_bf16 v[42:45], v[170:173], v[206:209], v[42:45]
	v_mfma_f32_16x16x32_bf16 v[30:33], v[152:155], v[210:213], v[30:33]
	v_mfma_f32_16x16x32_bf16 v[30:33], v[162:165], v[214:217], v[30:33]
	v_mfma_f32_16x16x32_bf16 v[26:29], v[166:169], v[210:213], v[26:29]
	v_mfma_f32_16x16x32_bf16 v[26:29], v[170:173], v[214:217], v[26:29]
	v_mfma_f32_16x16x32_bf16 v[14:17], v[152:155], v[218:221], v[14:17]
	v_mfma_f32_16x16x32_bf16 v[14:17], v[162:165], v[222:225], v[14:17]
	v_mfma_f32_16x16x32_bf16 v[10:13], v[166:169], v[218:221], v[10:13]
	v_mfma_f32_16x16x32_bf16 v[10:13], v[170:173], v[222:225], v[10:13]
	v_mfma_f32_16x16x32_bf16 v[54:57], v[174:177], v[194:197], v[54:57]
	v_mfma_f32_16x16x32_bf16 v[54:57], v[182:185], v[198:201], v[54:57]
	v_mfma_f32_16x16x32_bf16 v[50:53], v[186:189], v[194:197], v[50:53]
	v_mfma_f32_16x16x32_bf16 v[50:53], v[190:193], v[198:201], v[50:53]
	v_mfma_f32_16x16x32_bf16 v[38:41], v[174:177], v[202:205], v[38:41]
	v_mfma_f32_16x16x32_bf16 v[38:41], v[182:185], v[206:209], v[38:41]
	v_mfma_f32_16x16x32_bf16 v[34:37], v[186:189], v[202:205], v[34:37]
	v_mfma_f32_16x16x32_bf16 v[34:37], v[190:193], v[206:209], v[34:37]
	v_mfma_f32_16x16x32_bf16 v[22:25], v[174:177], v[210:213], v[22:25]
	v_mfma_f32_16x16x32_bf16 v[22:25], v[182:185], v[214:217], v[22:25]
	v_mfma_f32_16x16x32_bf16 v[18:21], v[186:189], v[210:213], v[18:21]
	v_mfma_f32_16x16x32_bf16 v[18:21], v[190:193], v[214:217], v[18:21]
	v_mfma_f32_16x16x32_bf16 v[6:9], v[174:177], v[218:221], v[6:9]
	v_mfma_f32_16x16x32_bf16 v[6:9], v[182:185], v[222:225], v[6:9]
	v_mfma_f32_16x16x32_bf16 v[2:5], v[186:189], v[218:221], v[2:5]
	v_mfma_f32_16x16x32_bf16 v[2:5], v[190:193], v[222:225], v[2:5]
	s_barrier
	s_add_i32 s35, s35, 2
	s_add_u32 s12, s12, 0x100
	s_addc_u32 s13, s13, 0
	s_add_u32 s0, s0, 0x100
	s_addc_u32 s1, s1, 0
	s_cmp_gt_u32 s35, 61
	s_cbranch_scc0 .LBB0_572
	s_and_b64 vcc, exec, s[10:11]
	s_cbranch_vccz .LBB0_575
	s_barrier

.LBB0_881:
	s_and_b32 s99, s28, 7
	s_lshl_b32 s99, s99, 5
	v_and_b32_e32 v244, 7, v0
	v_lshrrev_b32_e32 v245, 6, v0
	v_lshl_add_u32 v244, v245, 3, v244
	v_and_b32_e32 v245, 31, v244
	v_add_u32_e32 v245, s99, v245
	v_lshrrev_b32_e32 v246, 5, v244
	v_lshlrev_b32_e32 v245, 13, v245
	v_lshl_add_u32 v250, v246, 7, v245
	v_mov_b32_e32 v251, 0
	v_add_u32_e32 v252, 0x10000, v155
	s_add_u32 s10, s10, 0x100080
	s_addc_u32 s11, s11, 0
	s_add_u32 s0, s38, 0x100
	v_mov_b32_e32 v4, 0
	s_addc_u32 s1, s39, 0
	s_mov_b32 s12, -2
	v_mov_b32_e32 v5, v4
	v_mov_b32_e32 v6, v4
	v_mov_b32_e32 v7, v4
	v_mov_b32_e32 v8, v4
	v_mov_b32_e32 v9, v4
	v_mov_b32_e32 v10, v4
	v_mov_b32_e32 v11, v4
	v_mov_b32_e32 v20, v4
	v_mov_b32_e32 v21, v4
	v_mov_b32_e32 v22, v4
	v_mov_b32_e32 v23, v4
	v_mov_b32_e32 v24, v4
	v_mov_b32_e32 v25, v4
	v_mov_b32_e32 v26, v4
	v_mov_b32_e32 v27, v4
	v_mov_b32_e32 v36, v4
	v_mov_b32_e32 v37, v4
	v_mov_b32_e32 v38, v4
	v_mov_b32_e32 v39, v4
	v_mov_b32_e32 v40, v4
	v_mov_b32_e32 v41, v4
	v_mov_b32_e32 v42, v4
	v_mov_b32_e32 v43, v4
	v_mov_b32_e32 v52, v4
	v_mov_b32_e32 v53, v4
	v_mov_b32_e32 v54, v4
	v_mov_b32_e32 v55, v4
	v_mov_b32_e32 v56, v4
	v_mov_b32_e32 v57, v4
	v_mov_b32_e32 v58, v4
	v_mov_b32_e32 v59, v4
	v_mov_b32_e32 v12, v4
	v_mov_b32_e32 v13, v4
	v_mov_b32_e32 v14, v4
	v_mov_b32_e32 v15, v4
	v_mov_b32_e32 v16, v4
	v_mov_b32_e32 v17, v4
	v_mov_b32_e32 v18, v4
	v_mov_b32_e32 v19, v4
	v_mov_b32_e32 v28, v4
	v_mov_b32_e32 v29, v4
	v_mov_b32_e32 v30, v4
	v_mov_b32_e32 v31, v4
	v_mov_b32_e32 v32, v4
	v_mov_b32_e32 v33, v4
	v_mov_b32_e32 v34, v4
	v_mov_b32_e32 v35, v4
	v_mov_b32_e32 v44, v4
	v_mov_b32_e32 v45, v4
	v_mov_b32_e32 v46, v4
	v_mov_b32_e32 v47, v4
	v_mov_b32_e32 v48, v4
	v_mov_b32_e32 v49, v4
	v_mov_b32_e32 v50, v4
	v_mov_b32_e32 v51, v4
	v_mov_b32_e32 v60, v4
	v_mov_b32_e32 v61, v4
	v_mov_b32_e32 v62, v4
	v_mov_b32_e32 v63, v4
	v_mov_b32_e32 v64, v4
	v_mov_b32_e32 v65, v4
	v_mov_b32_e32 v66, v4
	v_mov_b32_e32 v67, v4
	v_mov_b32_e32 v68, v4
	v_mov_b32_e32 v69, v4
	v_mov_b32_e32 v70, v4
	v_mov_b32_e32 v71, v4
	v_mov_b32_e32 v72, v4
	v_mov_b32_e32 v73, v4
	v_mov_b32_e32 v74, v4
	v_mov_b32_e32 v75, v4
	v_mov_b32_e32 v84, v4
	v_mov_b32_e32 v85, v4
	v_mov_b32_e32 v86, v4
	v_mov_b32_e32 v87, v4
	v_mov_b32_e32 v88, v4
	v_mov_b32_e32 v89, v4
	v_mov_b32_e32 v90, v4
	v_mov_b32_e32 v91, v4
	v_mov_b32_e32 v100, v4
	v_mov_b32_e32 v101, v4
	v_mov_b32_e32 v102, v4
	v_mov_b32_e32 v103, v4
	v_mov_b32_e32 v104, v4
	v_mov_b32_e32 v105, v4
	v_mov_b32_e32 v106, v4
	v_mov_b32_e32 v107, v4
	v_mov_b32_e32 v116, v4
	v_mov_b32_e32 v117, v4
	v_mov_b32_e32 v118, v4
	v_mov_b32_e32 v119, v4
	v_mov_b32_e32 v120, v4
	v_mov_b32_e32 v121, v4
	v_mov_b32_e32 v122, v4
	v_mov_b32_e32 v123, v4
	v_mov_b32_e32 v76, v4
	v_mov_b32_e32 v77, v4
	v_mov_b32_e32 v78, v4
	v_mov_b32_e32 v79, v4
	v_mov_b32_e32 v80, v4
	v_mov_b32_e32 v81, v4
	v_mov_b32_e32 v82, v4
	v_mov_b32_e32 v83, v4
	v_mov_b32_e32 v92, v4
	v_mov_b32_e32 v93, v4
	v_mov_b32_e32 v94, v4
	v_mov_b32_e32 v95, v4
	v_mov_b32_e32 v96, v4
	v_mov_b32_e32 v97, v4
	v_mov_b32_e32 v98, v4
	v_mov_b32_e32 v99, v4
	v_mov_b32_e32 v108, v4
	v_mov_b32_e32 v109, v4
	v_mov_b32_e32 v110, v4
	v_mov_b32_e32 v111, v4
	v_mov_b32_e32 v112, v4
	v_mov_b32_e32 v113, v4
	v_mov_b32_e32 v114, v4
	v_mov_b32_e32 v115, v4
	v_mov_b32_e32 v124, v4
	v_mov_b32_e32 v125, v4
	v_mov_b32_e32 v126, v4
	v_mov_b32_e32 v127, v4
	v_mov_b32_e32 v128, v4
	v_mov_b32_e32 v129, v4
	v_mov_b32_e32 v130, v4
	v_mov_b32_e32 v131, v4
.LBB0_882:
	s_add_u32 s20, s10, 0xfff00080
	s_addc_u32 s21, s11, -1
	s_cmp_eq_u32 s12, 60
	s_cselect_b32 s43, s55, s21
	s_cselect_b32 s42, s54, s20
	s_cselect_b32 s39, s37, s1
	s_cselect_b32 s38, s36, s0
	v_lshl_add_u64 v[242:243], s[38:39], 0, v[250:251]
	s_add_i32 m0, s29, 0xc000
	ds_read_b128 v[146:149], v252
	ds_read_b128 v[150:153], v252 offset:1024
	global_load_lds_dwordx4 v140, s[10:11]
	s_add_i32 m0, s29, 0xe000
	ds_read_b128 v[158:161], v252 offset:2048
	ds_read_b128 v[162:165], v252 offset:3072
	global_load_lds_dwordx4 v142, s[10:11]
	ds_read_b128 v[166:169], v252 offset:16384
	ds_read_b128 v[170:173], v252 offset:17408
	ds_read_b128 v[174:177], v252 offset:18432
	ds_read_b128 v[186:189], v252 offset:19456
	ds_read_b128 v[190:193], v157
	ds_read_b128 v[194:197], v157 offset:1024
	ds_read_b128 v[198:201], v157 offset:2048
	ds_read_b128 v[202:205], v157 offset:3072
	ds_read_b128 v[206:209], v157 offset:4096
	ds_read_b128 v[210:213], v157 offset:5120
	ds_read_b128 v[214:217], v157 offset:6144
	ds_read_b128 v[218:221], v157 offset:7168
	s_waitcnt vmcnt(8)
	s_mov_b32 m0, 0x21800
	s_mov_b64 exec, 0xff
	s_waitcnt lgkmcnt(0)
	global_load_lds_dword v[242:243], off
	s_mov_b64 exec, -1
	s_barrier
	v_mfma_f32_16x16x32_bf16 v[128:131], v[146:149], v[190:193], v[128:131]
	v_mfma_f32_16x16x32_bf16 v[128:131], v[150:153], v[194:197], v[128:131]
	v_mfma_f32_16x16x32_bf16 v[124:127], v[158:161], v[190:193], v[124:127]
	v_mfma_f32_16x16x32_bf16 v[124:127], v[162:165], v[194:197], v[124:127]
	v_mfma_f32_16x16x32_bf16 v[112:115], v[146:149], v[198:201], v[112:115]
	v_mfma_f32_16x16x32_bf16 v[112:115], v[150:153], v[202:205], v[112:115]
	v_mfma_f32_16x16x32_bf16 v[108:111], v[158:161], v[198:201], v[108:111]
	v_mfma_f32_16x16x32_bf16 v[108:111], v[162:165], v[202:205], v[108:111]
	v_mfma_f32_16x16x32_bf16 v[96:99], v[146:149], v[206:209], v[96:99]
	v_mfma_f32_16x16x32_bf16 v[96:99], v[150:153], v[210:213], v[96:99]
	v_mfma_f32_16x16x32_bf16 v[92:95], v[158:161], v[206:209], v[92:95]
	v_mfma_f32_16x16x32_bf16 v[92:95], v[162:165], v[210:213], v[92:95]
	v_mfma_f32_16x16x32_bf16 v[80:83], v[146:149], v[214:217], v[80:83]
	v_mfma_f32_16x16x32_bf16 v[80:83], v[150:153], v[218:221], v[80:83]
	v_mfma_f32_16x16x32_bf16 v[76:79], v[158:161], v[214:217], v[76:79]
	v_mfma_f32_16x16x32_bf16 v[76:79], v[162:165], v[218:221], v[76:79]
	v_mfma_f32_16x16x32_bf16 v[120:123], v[166:169], v[190:193], v[120:123]
	v_mfma_f32_16x16x32_bf16 v[120:123], v[170:173], v[194:197], v[120:123]
	v_mfma_f32_16x16x32_bf16 v[116:119], v[174:177], v[190:193], v[116:119]
	v_mfma_f32_16x16x32_bf16 v[116:119], v[186:189], v[194:197], v[116:119]
	v_mfma_f32_16x16x32_bf16 v[104:107], v[166:169], v[198:201], v[104:107]
	v_mfma_f32_16x16x32_bf16 v[104:107], v[170:173], v[202:205], v[104:107]
	v_mfma_f32_16x16x32_bf16 v[100:103], v[174:177], v[198:201], v[100:103]
	v_mfma_f32_16x16x32_bf16 v[100:103], v[186:189], v[202:205], v[100:103]
	v_mfma_f32_16x16x32_bf16 v[88:91], v[166:169], v[206:209], v[88:91]
	v_mfma_f32_16x16x32_bf16 v[88:91], v[170:173], v[210:213], v[88:91]
	v_mfma_f32_16x16x32_bf16 v[84:87], v[174:177], v[206:209], v[84:87]
	v_mfma_f32_16x16x32_bf16 v[84:87], v[186:189], v[210:213], v[84:87]
	v_mfma_f32_16x16x32_bf16 v[72:75], v[166:169], v[214:217], v[72:75]
	v_mfma_f32_16x16x32_bf16 v[72:75], v[170:173], v[218:221], v[72:75]
	v_mfma_f32_16x16x32_bf16 v[68:71], v[174:177], v[214:217], v[68:71]
	v_mfma_f32_16x16x32_bf16 v[68:71], v[186:189], v[218:221], v[68:71]
	s_barrier
	s_add_i32 m0, s58, 0x10000
	ds_read_b128 v[190:193], v157 offset:16384
	ds_read_b128 v[194:197], v157 offset:17408
	global_load_lds_dwordx4 v134, s[38:39]
	s_add_i32 m0, s58, 0x12000
	s_add_u32 s98, s38, 0x100000
	s_addc_u32 s99, s39, 0
	ds_read_b128 v[198:201], v157 offset:18432
	global_load_lds_dwordx4 v138, s[38:39]
	s_add_i32 m0, s58, 0x14000
	ds_read_b128 v[202:205], v157 offset:19456
	ds_read_b128 v[206:209], v157 offset:20480
	global_load_lds_dwordx4 v134, s[98:99]
	s_add_i32 m0, s58, 0x16000
	ds_read_b128 v[210:213], v157 offset:21504
	ds_read_b128 v[214:217], v157 offset:22528
	global_load_lds_dwordx4 v138, s[98:99]
	s_mov_b32 m0, s29
	ds_read_b128 v[218:221], v157 offset:23552
	global_load_lds_dwordx4 v132, s[42:43]
	s_mov_b32 m0, s31
	s_nop 0
	global_load_lds_dwordx4 v136, s[42:43]
	s_waitcnt vmcnt(9)
	s_waitcnt lgkmcnt(0)
	s_barrier
	v_mfma_f32_16x16x32_bf16 v[64:67], v[146:149], v[190:193], v[64:67]
	v_mfma_f32_16x16x32_bf16 v[64:67], v[150:153], v[194:197], v[64:67]
	v_mfma_f32_16x16x32_bf16 v[60:63], v[158:161], v[190:193], v[60:63]
	v_mfma_f32_16x16x32_bf16 v[60:63], v[162:165], v[194:197], v[60:63]
	v_mfma_f32_16x16x32_bf16 v[48:51], v[146:149], v[198:201], v[48:51]
	v_mfma_f32_16x16x32_bf16 v[48:51], v[150:153], v[202:205], v[48:51]
	v_mfma_f32_16x16x32_bf16 v[44:47], v[158:161], v[198:201], v[44:47]
	v_mfma_f32_16x16x32_bf16 v[44:47], v[162:165], v[202:205], v[44:47]
	v_mfma_f32_16x16x32_bf16 v[32:35], v[146:149], v[206:209], v[32:35]
	v_mfma_f32_16x16x32_bf16 v[32:35], v[150:153], v[210:213], v[32:35]
	v_mfma_f32_16x16x32_bf16 v[28:31], v[158:161], v[206:209], v[28:31]
	v_mfma_f32_16x16x32_bf16 v[28:31], v[162:165], v[210:213], v[28:31]
	v_mfma_f32_16x16x32_bf16 v[16:19], v[146:149], v[214:217], v[16:19]
	v_mfma_f32_16x16x32_bf16 v[16:19], v[150:153], v[218:221], v[16:19]
	v_mfma_f32_16x16x32_bf16 v[12:15], v[158:161], v[214:217], v[12:15]
	v_mfma_f32_16x16x32_bf16 v[12:15], v[162:165], v[218:221], v[12:15]
	v_mfma_f32_16x16x32_bf16 v[56:59], v[166:169], v[190:193], v[56:59]
	v_mfma_f32_16x16x32_bf16 v[56:59], v[170:173], v[194:197], v[56:59]
	v_mfma_f32_16x16x32_bf16 v[52:55], v[174:177], v[190:193], v[52:55]
	v_mfma_f32_16x16x32_bf16 v[52:55], v[186:189], v[194:197], v[52:55]
	v_mfma_f32_16x16x32_bf16 v[40:43], v[166:169], v[198:201], v[40:43]
	v_mfma_f32_16x16x32_bf16 v[40:43], v[170:173], v[202:205], v[40:43]
	v_mfma_f32_16x16x32_bf16 v[36:39], v[174:177], v[198:201], v[36:39]
	v_mfma_f32_16x16x32_bf16 v[36:39], v[186:189], v[202:205], v[36:39]
	v_mfma_f32_16x16x32_bf16 v[24:27], v[166:169], v[206:209], v[24:27]
	v_mfma_f32_16x16x32_bf16 v[24:27], v[170:173], v[210:213], v[24:27]
	v_mfma_f32_16x16x32_bf16 v[20:23], v[174:177], v[206:209], v[20:23]
	v_mfma_f32_16x16x32_bf16 v[20:23], v[186:189], v[210:213], v[20:23]
	v_mfma_f32_16x16x32_bf16 v[8:11], v[166:169], v[214:217], v[8:11]
	v_mfma_f32_16x16x32_bf16 v[8:11], v[170:173], v[218:221], v[8:11]
	v_mfma_f32_16x16x32_bf16 v[4:7], v[174:177], v[214:217], v[4:7]
	v_mfma_f32_16x16x32_bf16 v[4:7], v[186:189], v[218:221], v[4:7]
	s_barrier
	s_add_u32 s100, s42, 0x100000
	s_addc_u32 s101, s43, 0
	s_mov_b32 m0, s59
	ds_read_b128 v[146:149], v252 offset:32768
	ds_read_b128 v[150:153], v252 offset:33792
	global_load_lds_dwordx4 v132, s[100:101]
	s_mov_b32 m0, s94
	ds_read_b128 v[158:161], v252 offset:34816
	ds_read_b128 v[162:165], v252 offset:35840
	global_load_lds_dwordx4 v136, s[100:101]
	ds_read_b128 v[166:169], v252 offset:49152
	ds_read_b128 v[170:173], v252 offset:50176
	ds_read_b128 v[174:177], v252 offset:51200
	ds_read_b128 v[186:189], v252 offset:52224
	ds_read_b128 v[190:193], v157 offset:32768
	ds_read_b128 v[194:197], v157 offset:33792
	ds_read_b128 v[198:201], v157 offset:34816
	ds_read_b128 v[202:205], v157 offset:35840
	ds_read_b128 v[206:209], v157 offset:36864
	ds_read_b128 v[210:213], v157 offset:37888
	ds_read_b128 v[214:217], v157 offset:38912
	ds_read_b128 v[218:221], v157 offset:39936
	s_waitcnt vmcnt(9)
	s_waitcnt lgkmcnt(0)
	s_barrier
	v_mfma_f32_16x16x32_bf16 v[128:131], v[146:149], v[190:193], v[128:131]
	v_mfma_f32_16x16x32_bf16 v[128:131], v[150:153], v[194:197], v[128:131]
	v_mfma_f32_16x16x32_bf16 v[124:127], v[158:161], v[190:193], v[124:127]
	v_mfma_f32_16x16x32_bf16 v[124:127], v[162:165], v[194:197], v[124:127]
	v_mfma_f32_16x16x32_bf16 v[112:115], v[146:149], v[198:201], v[112:115]
	v_mfma_f32_16x16x32_bf16 v[112:115], v[150:153], v[202:205], v[112:115]
	v_mfma_f32_16x16x32_bf16 v[108:111], v[158:161], v[198:201], v[108:111]
	v_mfma_f32_16x16x32_bf16 v[108:111], v[162:165], v[202:205], v[108:111]
	v_mfma_f32_16x16x32_bf16 v[96:99], v[146:149], v[206:209], v[96:99]
	v_mfma_f32_16x16x32_bf16 v[96:99], v[150:153], v[210:213], v[96:99]
	v_mfma_f32_16x16x32_bf16 v[92:95], v[158:161], v[206:209], v[92:95]
	v_mfma_f32_16x16x32_bf16 v[92:95], v[162:165], v[210:213], v[92:95]
	v_mfma_f32_16x16x32_bf16 v[80:83], v[146:149], v[214:217], v[80:83]
	v_mfma_f32_16x16x32_bf16 v[80:83], v[150:153], v[218:221], v[80:83]
	v_mfma_f32_16x16x32_bf16 v[76:79], v[158:161], v[214:217], v[76:79]
	v_mfma_f32_16x16x32_bf16 v[76:79], v[162:165], v[218:221], v[76:79]
	v_mfma_f32_16x16x32_bf16 v[120:123], v[166:169], v[190:193], v[120:123]
	v_mfma_f32_16x16x32_bf16 v[120:123], v[170:173], v[194:197], v[120:123]
	v_mfma_f32_16x16x32_bf16 v[116:119], v[174:177], v[190:193], v[116:119]
	v_mfma_f32_16x16x32_bf16 v[116:119], v[186:189], v[194:197], v[116:119]
	v_mfma_f32_16x16x32_bf16 v[104:107], v[166:169], v[198:201], v[104:107]
	v_mfma_f32_16x16x32_bf16 v[104:107], v[170:173], v[202:205], v[104:107]
	v_mfma_f32_16x16x32_bf16 v[100:103], v[174:177], v[198:201], v[100:103]
	v_mfma_f32_16x16x32_bf16 v[100:103], v[186:189], v[202:205], v[100:103]
	v_mfma_f32_16x16x32_bf16 v[88:91], v[166:169], v[206:209], v[88:91]
	v_mfma_f32_16x16x32_bf16 v[88:91], v[170:173], v[210:213], v[88:91]
	v_mfma_f32_16x16x32_bf16 v[84:87], v[174:177], v[206:209], v[84:87]
	v_mfma_f32_16x16x32_bf16 v[84:87], v[186:189], v[210:213], v[84:87]
	v_mfma_f32_16x16x32_bf16 v[72:75], v[166:169], v[214:217], v[72:75]
	v_mfma_f32_16x16x32_bf16 v[72:75], v[170:173], v[218:221], v[72:75]
	v_mfma_f32_16x16x32_bf16 v[68:71], v[174:177], v[214:217], v[68:71]
	v_mfma_f32_16x16x32_bf16 v[68:71], v[186:189], v[218:221], v[68:71]
	s_barrier
	s_add_u32 s38, s38, 0x80
	s_addc_u32 s39, s39, 0
	s_add_i32 m0, s58, 0x18000
	ds_read_b128 v[190:193], v157 offset:49152
	ds_read_b128 v[194:197], v157 offset:50176
	global_load_lds_dwordx4 v134, s[38:39]
	s_add_i32 m0, s58, 0x1a000
	s_add_u32 s98, s98, 0x80
	s_addc_u32 s99, s99, 0
	ds_read_b128 v[198:201], v157 offset:51200
	global_load_lds_dwordx4 v138, s[38:39]
	s_add_i32 m0, s58, 0x1c000
	ds_read_b128 v[202:205], v157 offset:52224
	ds_read_b128 v[206:209], v157 offset:53248
	global_load_lds_dwordx4 v134, s[98:99]
	s_add_i32 m0, s58, 0x1e000
	s_add_u32 s42, s42, 0x80
	s_addc_u32 s43, s43, 0
	ds_read_b128 v[210:213], v157 offset:54272
	ds_read_b128 v[214:217], v157 offset:55296
	global_load_lds_dwordx4 v138, s[98:99]
	s_mov_b32 m0, s14
	ds_read_b128 v[218:221], v157 offset:56320
	global_load_lds_dwordx4 v132, s[42:43]
	s_mov_b32 m0, s15
	s_nop 0
	global_load_lds_dwordx4 v136, s[42:43]
	s_waitcnt vmcnt(8)
	s_waitcnt lgkmcnt(0)
	s_barrier
	v_mfma_f32_16x16x32_bf16 v[64:67], v[146:149], v[190:193], v[64:67]
	v_mfma_f32_16x16x32_bf16 v[64:67], v[150:153], v[194:197], v[64:67]
	v_mfma_f32_16x16x32_bf16 v[60:63], v[158:161], v[190:193], v[60:63]
	v_mfma_f32_16x16x32_bf16 v[60:63], v[162:165], v[194:197], v[60:63]
	v_mfma_f32_16x16x32_bf16 v[48:51], v[146:149], v[198:201], v[48:51]
	v_mfma_f32_16x16x32_bf16 v[48:51], v[150:153], v[202:205], v[48:51]
	v_mfma_f32_16x16x32_bf16 v[44:47], v[158:161], v[198:201], v[44:47]
	v_mfma_f32_16x16x32_bf16 v[44:47], v[162:165], v[202:205], v[44:47]
	v_mfma_f32_16x16x32_bf16 v[32:35], v[146:149], v[206:209], v[32:35]
	v_mfma_f32_16x16x32_bf16 v[32:35], v[150:153], v[210:213], v[32:35]
	v_mfma_f32_16x16x32_bf16 v[28:31], v[158:161], v[206:209], v[28:31]
	v_mfma_f32_16x16x32_bf16 v[28:31], v[162:165], v[210:213], v[28:31]
	v_mfma_f32_16x16x32_bf16 v[16:19], v[146:149], v[214:217], v[16:19]
	v_mfma_f32_16x16x32_bf16 v[16:19], v[150:153], v[218:221], v[16:19]
	v_mfma_f32_16x16x32_bf16 v[12:15], v[158:161], v[214:217], v[12:15]
	v_mfma_f32_16x16x32_bf16 v[12:15], v[162:165], v[218:221], v[12:15]
	v_mfma_f32_16x16x32_bf16 v[56:59], v[166:169], v[190:193], v[56:59]
	v_mfma_f32_16x16x32_bf16 v[56:59], v[170:173], v[194:197], v[56:59]
	v_mfma_f32_16x16x32_bf16 v[52:55], v[174:177], v[190:193], v[52:55]
	v_mfma_f32_16x16x32_bf16 v[52:55], v[186:189], v[194:197], v[52:55]
	v_mfma_f32_16x16x32_bf16 v[40:43], v[166:169], v[198:201], v[40:43]
	v_mfma_f32_16x16x32_bf16 v[40:43], v[170:173], v[202:205], v[40:43]
	v_mfma_f32_16x16x32_bf16 v[36:39], v[174:177], v[198:201], v[36:39]
	v_mfma_f32_16x16x32_bf16 v[36:39], v[186:189], v[202:205], v[36:39]
	v_mfma_f32_16x16x32_bf16 v[24:27], v[166:169], v[206:209], v[24:27]
	v_mfma_f32_16x16x32_bf16 v[24:27], v[170:173], v[210:213], v[24:27]
	v_mfma_f32_16x16x32_bf16 v[20:23], v[174:177], v[206:209], v[20:23]
	v_mfma_f32_16x16x32_bf16 v[20:23], v[186:189], v[210:213], v[20:23]
	v_mfma_f32_16x16x32_bf16 v[8:11], v[166:169], v[214:217], v[8:11]
	v_mfma_f32_16x16x32_bf16 v[8:11], v[170:173], v[218:221], v[8:11]
	v_mfma_f32_16x16x32_bf16 v[4:7], v[174:177], v[214:217], v[4:7]
	v_mfma_f32_16x16x32_bf16 v[4:7], v[186:189], v[218:221], v[4:7]
	s_barrier
	s_add_i32 s12, s12, 2
	s_add_u32 s10, s10, 0x100
	s_addc_u32 s11, s11, 0
	s_add_u32 s0, s0, 0x100
	s_addc_u32 s1, s1, 0
	s_cmp_gt_u32 s12, 61
	s_cbranch_scc0 .LBB0_882
	s_and_b64 vcc, exec, s[48:49]
	s_cbranch_vccz .LBB0_885
	s_barrier

.LBB0_1225:
	s_and_b32 s99, s58, 7
	s_lshl_b32 s99, s99, 5
	v_and_b32_e32 v244, 7, v0
	v_lshrrev_b32_e32 v245, 6, v0
	v_lshl_add_u32 v244, v245, 3, v244
	v_and_b32_e32 v245, 31, v244
	v_add_u32_e32 v245, s99, v245
	v_lshrrev_b32_e32 v246, 5, v244
	v_lshlrev_b32_e32 v245, 13, v245
	v_lshl_add_u32 v250, v246, 7, v245
	v_mov_b32_e32 v251, 0
	v_add_u32_e32 v252, 0x10000, v151
	s_add_u32 s10, s10, 0x100080
	s_addc_u32 s11, s11, 0
	s_add_u32 s0, s28, 0x100
	v_mov_b32_e32 v4, 0
	s_addc_u32 s1, s29, 0
	s_mov_b32 s20, -2
	v_mov_b32_e32 v5, v4
	v_mov_b32_e32 v6, v4
	v_mov_b32_e32 v7, v4
	v_mov_b32_e32 v8, v4
	v_mov_b32_e32 v9, v4
	v_mov_b32_e32 v10, v4
	v_mov_b32_e32 v11, v4
	v_mov_b32_e32 v20, v4
	v_mov_b32_e32 v21, v4
	v_mov_b32_e32 v22, v4
	v_mov_b32_e32 v23, v4
	v_mov_b32_e32 v24, v4
	v_mov_b32_e32 v25, v4
	v_mov_b32_e32 v26, v4
	v_mov_b32_e32 v27, v4
	v_mov_b32_e32 v36, v4
	v_mov_b32_e32 v37, v4
	v_mov_b32_e32 v38, v4
	v_mov_b32_e32 v39, v4
	v_mov_b32_e32 v40, v4
	v_mov_b32_e32 v41, v4
	v_mov_b32_e32 v42, v4
	v_mov_b32_e32 v43, v4
	v_mov_b32_e32 v52, v4
	v_mov_b32_e32 v53, v4
	v_mov_b32_e32 v54, v4
	v_mov_b32_e32 v55, v4
	v_mov_b32_e32 v56, v4
	v_mov_b32_e32 v57, v4
	v_mov_b32_e32 v58, v4
	v_mov_b32_e32 v59, v4
	v_mov_b32_e32 v12, v4
	v_mov_b32_e32 v13, v4
	v_mov_b32_e32 v14, v4
	v_mov_b32_e32 v15, v4
	v_mov_b32_e32 v16, v4
	v_mov_b32_e32 v17, v4
	v_mov_b32_e32 v18, v4
	v_mov_b32_e32 v19, v4
	v_mov_b32_e32 v28, v4
	v_mov_b32_e32 v29, v4
	v_mov_b32_e32 v30, v4
	v_mov_b32_e32 v31, v4
	v_mov_b32_e32 v32, v4
	v_mov_b32_e32 v33, v4
	v_mov_b32_e32 v34, v4
	v_mov_b32_e32 v35, v4
	v_mov_b32_e32 v44, v4
	v_mov_b32_e32 v45, v4
	v_mov_b32_e32 v46, v4
	v_mov_b32_e32 v47, v4
	v_mov_b32_e32 v48, v4
	v_mov_b32_e32 v49, v4
	v_mov_b32_e32 v50, v4
	v_mov_b32_e32 v51, v4
	v_mov_b32_e32 v60, v4
	v_mov_b32_e32 v61, v4
	v_mov_b32_e32 v62, v4
	v_mov_b32_e32 v63, v4
	v_mov_b32_e32 v64, v4
	v_mov_b32_e32 v65, v4
	v_mov_b32_e32 v66, v4
	v_mov_b32_e32 v67, v4
	v_mov_b32_e32 v68, v4
	v_mov_b32_e32 v69, v4
	v_mov_b32_e32 v70, v4
	v_mov_b32_e32 v71, v4
	v_mov_b32_e32 v72, v4
	v_mov_b32_e32 v73, v4
	v_mov_b32_e32 v74, v4
	v_mov_b32_e32 v75, v4
	v_mov_b32_e32 v84, v4
	v_mov_b32_e32 v85, v4
	v_mov_b32_e32 v86, v4
	v_mov_b32_e32 v87, v4
	v_mov_b32_e32 v88, v4
	v_mov_b32_e32 v89, v4
	v_mov_b32_e32 v90, v4
	v_mov_b32_e32 v91, v4
	v_mov_b32_e32 v100, v4
	v_mov_b32_e32 v101, v4
	v_mov_b32_e32 v102, v4
	v_mov_b32_e32 v103, v4
	v_mov_b32_e32 v104, v4
	v_mov_b32_e32 v105, v4
	v_mov_b32_e32 v106, v4
	v_mov_b32_e32 v107, v4
	v_mov_b32_e32 v116, v4
	v_mov_b32_e32 v117, v4
	v_mov_b32_e32 v118, v4
	v_mov_b32_e32 v119, v4
	v_mov_b32_e32 v120, v4
	v_mov_b32_e32 v121, v4
	v_mov_b32_e32 v122, v4
	v_mov_b32_e32 v123, v4
	v_mov_b32_e32 v76, v4
	v_mov_b32_e32 v77, v4
	v_mov_b32_e32 v78, v4
	v_mov_b32_e32 v79, v4
	v_mov_b32_e32 v80, v4
	v_mov_b32_e32 v81, v4
	v_mov_b32_e32 v82, v4
	v_mov_b32_e32 v83, v4
	v_mov_b32_e32 v92, v4
	v_mov_b32_e32 v93, v4
	v_mov_b32_e32 v94, v4
	v_mov_b32_e32 v95, v4
	v_mov_b32_e32 v96, v4
	v_mov_b32_e32 v97, v4
	v_mov_b32_e32 v98, v4
	v_mov_b32_e32 v99, v4
	v_mov_b32_e32 v108, v4
	v_mov_b32_e32 v109, v4
	v_mov_b32_e32 v110, v4
	v_mov_b32_e32 v111, v4
	v_mov_b32_e32 v112, v4
	v_mov_b32_e32 v113, v4
	v_mov_b32_e32 v114, v4
	v_mov_b32_e32 v115, v4
	v_mov_b32_e32 v124, v4
	v_mov_b32_e32 v125, v4
	v_mov_b32_e32 v126, v4
	v_mov_b32_e32 v127, v4
	v_mov_b32_e32 v128, v4
	v_mov_b32_e32 v129, v4
	v_mov_b32_e32 v130, v4
	v_mov_b32_e32 v131, v4
.LBB0_1226:
	s_add_u32 s21, s10, 0xfff00080
	s_addc_u32 s22, s11, -1
	s_cmp_eq_u32 s20, 60
	s_cselect_b32 s31, s53, s22
	s_cselect_b32 s30, s52, s21
	s_cselect_b32 s29, s55, s1
	s_cselect_b32 s28, s54, s0
	v_lshl_add_u64 v[242:243], s[28:29], 0, v[250:251]
	s_add_i32 m0, s8, 0xc000
	ds_read_b128 v[144:147], v252
	ds_read_b128 v[154:157], v252 offset:1024
	global_load_lds_dwordx4 v140, s[10:11]
	s_add_i32 m0, s8, 0xe000
	ds_read_b128 v[158:161], v252 offset:2048
	ds_read_b128 v[162:165], v252 offset:3072
	global_load_lds_dwordx4 v142, s[10:11]
	ds_read_b128 v[166:169], v252 offset:16384
	ds_read_b128 v[170:173], v252 offset:17408
	ds_read_b128 v[174:177], v252 offset:18432
	ds_read_b128 v[186:189], v252 offset:19456
	ds_read_b128 v[190:193], v153
	ds_read_b128 v[194:197], v153 offset:1024
	ds_read_b128 v[198:201], v153 offset:2048
	ds_read_b128 v[202:205], v153 offset:3072
	ds_read_b128 v[206:209], v153 offset:4096
	ds_read_b128 v[210:213], v153 offset:5120
	ds_read_b128 v[214:217], v153 offset:6144
	ds_read_b128 v[218:221], v153 offset:7168
	s_waitcnt vmcnt(8)
	s_mov_b32 m0, 0x21800
	s_mov_b64 exec, 0xff
	s_waitcnt lgkmcnt(0)
	global_load_lds_dword v[242:243], off
	s_mov_b64 exec, -1
	s_barrier
	v_mfma_f32_16x16x32_bf16 v[128:131], v[144:147], v[190:193], v[128:131]
	v_mfma_f32_16x16x32_bf16 v[128:131], v[154:157], v[194:197], v[128:131]
	v_mfma_f32_16x16x32_bf16 v[124:127], v[158:161], v[190:193], v[124:127]
	v_mfma_f32_16x16x32_bf16 v[124:127], v[162:165], v[194:197], v[124:127]
	v_mfma_f32_16x16x32_bf16 v[112:115], v[144:147], v[198:201], v[112:115]
	v_mfma_f32_16x16x32_bf16 v[112:115], v[154:157], v[202:205], v[112:115]
	v_mfma_f32_16x16x32_bf16 v[108:111], v[158:161], v[198:201], v[108:111]
	v_mfma_f32_16x16x32_bf16 v[108:111], v[162:165], v[202:205], v[108:111]
	v_mfma_f32_16x16x32_bf16 v[96:99], v[144:147], v[206:209], v[96:99]
	v_mfma_f32_16x16x32_bf16 v[96:99], v[154:157], v[210:213], v[96:99]
	v_mfma_f32_16x16x32_bf16 v[92:95], v[158:161], v[206:209], v[92:95]
	v_mfma_f32_16x16x32_bf16 v[92:95], v[162:165], v[210:213], v[92:95]
	v_mfma_f32_16x16x32_bf16 v[80:83], v[144:147], v[214:217], v[80:83]
	v_mfma_f32_16x16x32_bf16 v[80:83], v[154:157], v[218:221], v[80:83]
	v_mfma_f32_16x16x32_bf16 v[76:79], v[158:161], v[214:217], v[76:79]
	v_mfma_f32_16x16x32_bf16 v[76:79], v[162:165], v[218:221], v[76:79]
	v_mfma_f32_16x16x32_bf16 v[120:123], v[166:169], v[190:193], v[120:123]
	v_mfma_f32_16x16x32_bf16 v[120:123], v[170:173], v[194:197], v[120:123]
	v_mfma_f32_16x16x32_bf16 v[116:119], v[174:177], v[190:193], v[116:119]
	v_mfma_f32_16x16x32_bf16 v[116:119], v[186:189], v[194:197], v[116:119]
	v_mfma_f32_16x16x32_bf16 v[104:107], v[166:169], v[198:201], v[104:107]
	v_mfma_f32_16x16x32_bf16 v[104:107], v[170:173], v[202:205], v[104:107]
	v_mfma_f32_16x16x32_bf16 v[100:103], v[174:177], v[198:201], v[100:103]
	v_mfma_f32_16x16x32_bf16 v[100:103], v[186:189], v[202:205], v[100:103]
	v_mfma_f32_16x16x32_bf16 v[88:91], v[166:169], v[206:209], v[88:91]
	v_mfma_f32_16x16x32_bf16 v[88:91], v[170:173], v[210:213], v[88:91]
	v_mfma_f32_16x16x32_bf16 v[84:87], v[174:177], v[206:209], v[84:87]
	v_mfma_f32_16x16x32_bf16 v[84:87], v[186:189], v[210:213], v[84:87]
	v_mfma_f32_16x16x32_bf16 v[72:75], v[166:169], v[214:217], v[72:75]
	v_mfma_f32_16x16x32_bf16 v[72:75], v[170:173], v[218:221], v[72:75]
	v_mfma_f32_16x16x32_bf16 v[68:71], v[174:177], v[214:217], v[68:71]
	v_mfma_f32_16x16x32_bf16 v[68:71], v[186:189], v[218:221], v[68:71]
	s_barrier
	s_add_i32 m0, s38, 0x10000
	ds_read_b128 v[190:193], v153 offset:16384
	ds_read_b128 v[194:197], v153 offset:17408
	global_load_lds_dwordx4 v136, s[28:29]
	s_add_i32 m0, s38, 0x12000
	s_add_u32 s98, s28, 0x100000
	s_addc_u32 s99, s29, 0
	ds_read_b128 v[198:201], v153 offset:18432
	global_load_lds_dwordx4 v132, s[28:29]
	s_add_i32 m0, s38, 0x14000
	ds_read_b128 v[202:205], v153 offset:19456
	ds_read_b128 v[206:209], v153 offset:20480
	global_load_lds_dwordx4 v136, s[98:99]
	s_add_i32 m0, s38, 0x16000
	ds_read_b128 v[210:213], v153 offset:21504
	ds_read_b128 v[214:217], v153 offset:22528
	global_load_lds_dwordx4 v132, s[98:99]
	s_mov_b32 m0, s8
	ds_read_b128 v[218:221], v153 offset:23552
	global_load_lds_dwordx4 v138, s[30:31]
	s_mov_b32 m0, s9
	s_nop 0
	global_load_lds_dwordx4 v134, s[30:31]
	s_waitcnt vmcnt(9)
	s_waitcnt lgkmcnt(0)
	s_barrier
	v_mfma_f32_16x16x32_bf16 v[64:67], v[144:147], v[190:193], v[64:67]
	v_mfma_f32_16x16x32_bf16 v[64:67], v[154:157], v[194:197], v[64:67]
	v_mfma_f32_16x16x32_bf16 v[60:63], v[158:161], v[190:193], v[60:63]
	v_mfma_f32_16x16x32_bf16 v[60:63], v[162:165], v[194:197], v[60:63]
	v_mfma_f32_16x16x32_bf16 v[48:51], v[144:147], v[198:201], v[48:51]
	v_mfma_f32_16x16x32_bf16 v[48:51], v[154:157], v[202:205], v[48:51]
	v_mfma_f32_16x16x32_bf16 v[44:47], v[158:161], v[198:201], v[44:47]
	v_mfma_f32_16x16x32_bf16 v[44:47], v[162:165], v[202:205], v[44:47]
	v_mfma_f32_16x16x32_bf16 v[32:35], v[144:147], v[206:209], v[32:35]
	v_mfma_f32_16x16x32_bf16 v[32:35], v[154:157], v[210:213], v[32:35]
	v_mfma_f32_16x16x32_bf16 v[28:31], v[158:161], v[206:209], v[28:31]
	v_mfma_f32_16x16x32_bf16 v[28:31], v[162:165], v[210:213], v[28:31]
	v_mfma_f32_16x16x32_bf16 v[16:19], v[144:147], v[214:217], v[16:19]
	v_mfma_f32_16x16x32_bf16 v[16:19], v[154:157], v[218:221], v[16:19]
	v_mfma_f32_16x16x32_bf16 v[12:15], v[158:161], v[214:217], v[12:15]
	v_mfma_f32_16x16x32_bf16 v[12:15], v[162:165], v[218:221], v[12:15]
	v_mfma_f32_16x16x32_bf16 v[56:59], v[166:169], v[190:193], v[56:59]
	v_mfma_f32_16x16x32_bf16 v[56:59], v[170:173], v[194:197], v[56:59]
	v_mfma_f32_16x16x32_bf16 v[52:55], v[174:177], v[190:193], v[52:55]
	v_mfma_f32_16x16x32_bf16 v[52:55], v[186:189], v[194:197], v[52:55]
	v_mfma_f32_16x16x32_bf16 v[40:43], v[166:169], v[198:201], v[40:43]
	v_mfma_f32_16x16x32_bf16 v[40:43], v[170:173], v[202:205], v[40:43]
	v_mfma_f32_16x16x32_bf16 v[36:39], v[174:177], v[198:201], v[36:39]
	v_mfma_f32_16x16x32_bf16 v[36:39], v[186:189], v[202:205], v[36:39]
	v_mfma_f32_16x16x32_bf16 v[24:27], v[166:169], v[206:209], v[24:27]
	v_mfma_f32_16x16x32_bf16 v[24:27], v[170:173], v[210:213], v[24:27]
	v_mfma_f32_16x16x32_bf16 v[20:23], v[174:177], v[206:209], v[20:23]
	v_mfma_f32_16x16x32_bf16 v[20:23], v[186:189], v[210:213], v[20:23]
	v_mfma_f32_16x16x32_bf16 v[8:11], v[166:169], v[214:217], v[8:11]
	v_mfma_f32_16x16x32_bf16 v[8:11], v[170:173], v[218:221], v[8:11]
	v_mfma_f32_16x16x32_bf16 v[4:7], v[174:177], v[214:217], v[4:7]
	v_mfma_f32_16x16x32_bf16 v[4:7], v[186:189], v[218:221], v[4:7]
	s_barrier
	s_add_u32 s100, s30, 0x100000
	s_addc_u32 s101, s31, 0
	s_mov_b32 m0, s16
	ds_read_b128 v[144:147], v252 offset:32768
	ds_read_b128 v[154:157], v252 offset:33792
	global_load_lds_dwordx4 v138, s[100:101]
	s_mov_b32 m0, s17
	ds_read_b128 v[158:161], v252 offset:34816
	ds_read_b128 v[162:165], v252 offset:35840
	global_load_lds_dwordx4 v134, s[100:101]
	ds_read_b128 v[166:169], v252 offset:49152
	ds_read_b128 v[170:173], v252 offset:50176
	ds_read_b128 v[174:177], v252 offset:51200
	ds_read_b128 v[186:189], v252 offset:52224
	ds_read_b128 v[190:193], v153 offset:32768
	ds_read_b128 v[194:197], v153 offset:33792
	ds_read_b128 v[198:201], v153 offset:34816
	ds_read_b128 v[202:205], v153 offset:35840
	ds_read_b128 v[206:209], v153 offset:36864
	ds_read_b128 v[210:213], v153 offset:37888
	ds_read_b128 v[214:217], v153 offset:38912
	ds_read_b128 v[218:221], v153 offset:39936
	s_waitcnt vmcnt(9)
	s_waitcnt lgkmcnt(0)
	s_barrier
	v_mfma_f32_16x16x32_bf16 v[128:131], v[144:147], v[190:193], v[128:131]
	v_mfma_f32_16x16x32_bf16 v[128:131], v[154:157], v[194:197], v[128:131]
	v_mfma_f32_16x16x32_bf16 v[124:127], v[158:161], v[190:193], v[124:127]
	v_mfma_f32_16x16x32_bf16 v[124:127], v[162:165], v[194:197], v[124:127]
	v_mfma_f32_16x16x32_bf16 v[112:115], v[144:147], v[198:201], v[112:115]
	v_mfma_f32_16x16x32_bf16 v[112:115], v[154:157], v[202:205], v[112:115]
	v_mfma_f32_16x16x32_bf16 v[108:111], v[158:161], v[198:201], v[108:111]
	v_mfma_f32_16x16x32_bf16 v[108:111], v[162:165], v[202:205], v[108:111]
	v_mfma_f32_16x16x32_bf16 v[96:99], v[144:147], v[206:209], v[96:99]
	v_mfma_f32_16x16x32_bf16 v[96:99], v[154:157], v[210:213], v[96:99]
	v_mfma_f32_16x16x32_bf16 v[92:95], v[158:161], v[206:209], v[92:95]
	v_mfma_f32_16x16x32_bf16 v[92:95], v[162:165], v[210:213], v[92:95]
	v_mfma_f32_16x16x32_bf16 v[80:83], v[144:147], v[214:217], v[80:83]
	v_mfma_f32_16x16x32_bf16 v[80:83], v[154:157], v[218:221], v[80:83]
	v_mfma_f32_16x16x32_bf16 v[76:79], v[158:161], v[214:217], v[76:79]
	v_mfma_f32_16x16x32_bf16 v[76:79], v[162:165], v[218:221], v[76:79]
	v_mfma_f32_16x16x32_bf16 v[120:123], v[166:169], v[190:193], v[120:123]
	v_mfma_f32_16x16x32_bf16 v[120:123], v[170:173], v[194:197], v[120:123]
	v_mfma_f32_16x16x32_bf16 v[116:119], v[174:177], v[190:193], v[116:119]
	v_mfma_f32_16x16x32_bf16 v[116:119], v[186:189], v[194:197], v[116:119]
	v_mfma_f32_16x16x32_bf16 v[104:107], v[166:169], v[198:201], v[104:107]
	v_mfma_f32_16x16x32_bf16 v[104:107], v[170:173], v[202:205], v[104:107]
	v_mfma_f32_16x16x32_bf16 v[100:103], v[174:177], v[198:201], v[100:103]
	v_mfma_f32_16x16x32_bf16 v[100:103], v[186:189], v[202:205], v[100:103]
	v_mfma_f32_16x16x32_bf16 v[88:91], v[166:169], v[206:209], v[88:91]
	v_mfma_f32_16x16x32_bf16 v[88:91], v[170:173], v[210:213], v[88:91]
	v_mfma_f32_16x16x32_bf16 v[84:87], v[174:177], v[206:209], v[84:87]
	v_mfma_f32_16x16x32_bf16 v[84:87], v[186:189], v[210:213], v[84:87]
	v_mfma_f32_16x16x32_bf16 v[72:75], v[166:169], v[214:217], v[72:75]
	v_mfma_f32_16x16x32_bf16 v[72:75], v[170:173], v[218:221], v[72:75]
	v_mfma_f32_16x16x32_bf16 v[68:71], v[174:177], v[214:217], v[68:71]
	v_mfma_f32_16x16x32_bf16 v[68:71], v[186:189], v[218:221], v[68:71]
	s_barrier
	s_add_u32 s28, s28, 0x80
	s_addc_u32 s29, s29, 0
	s_add_i32 m0, s38, 0x18000
	ds_read_b128 v[190:193], v153 offset:49152
	ds_read_b128 v[194:197], v153 offset:50176
	global_load_lds_dwordx4 v136, s[28:29]
	s_add_i32 m0, s38, 0x1a000
	s_add_u32 s98, s98, 0x80
	s_addc_u32 s99, s99, 0
	ds_read_b128 v[198:201], v153 offset:51200
	global_load_lds_dwordx4 v132, s[28:29]
	s_add_i32 m0, s38, 0x1c000
	ds_read_b128 v[202:205], v153 offset:52224
	ds_read_b128 v[206:209], v153 offset:53248
	global_load_lds_dwordx4 v136, s[98:99]
	s_add_i32 m0, s38, 0x1e000
	s_add_u32 s30, s30, 0x80
	s_addc_u32 s31, s31, 0
	ds_read_b128 v[210:213], v153 offset:54272
	ds_read_b128 v[214:217], v153 offset:55296
	global_load_lds_dwordx4 v132, s[98:99]
	s_mov_b32 m0, s45
	ds_read_b128 v[218:221], v153 offset:56320
	global_load_lds_dwordx4 v138, s[30:31]
	s_mov_b32 m0, s46
	s_nop 0
	global_load_lds_dwordx4 v134, s[30:31]
	s_waitcnt vmcnt(8)
	s_waitcnt lgkmcnt(0)
	s_barrier
	v_mfma_f32_16x16x32_bf16 v[64:67], v[144:147], v[190:193], v[64:67]
	v_mfma_f32_16x16x32_bf16 v[64:67], v[154:157], v[194:197], v[64:67]
	v_mfma_f32_16x16x32_bf16 v[60:63], v[158:161], v[190:193], v[60:63]
	v_mfma_f32_16x16x32_bf16 v[60:63], v[162:165], v[194:197], v[60:63]
	v_mfma_f32_16x16x32_bf16 v[48:51], v[144:147], v[198:201], v[48:51]
	v_mfma_f32_16x16x32_bf16 v[48:51], v[154:157], v[202:205], v[48:51]
	v_mfma_f32_16x16x32_bf16 v[44:47], v[158:161], v[198:201], v[44:47]
	v_mfma_f32_16x16x32_bf16 v[44:47], v[162:165], v[202:205], v[44:47]
	v_mfma_f32_16x16x32_bf16 v[32:35], v[144:147], v[206:209], v[32:35]
	v_mfma_f32_16x16x32_bf16 v[32:35], v[154:157], v[210:213], v[32:35]
	v_mfma_f32_16x16x32_bf16 v[28:31], v[158:161], v[206:209], v[28:31]
	v_mfma_f32_16x16x32_bf16 v[28:31], v[162:165], v[210:213], v[28:31]
	v_mfma_f32_16x16x32_bf16 v[16:19], v[144:147], v[214:217], v[16:19]
	v_mfma_f32_16x16x32_bf16 v[16:19], v[154:157], v[218:221], v[16:19]
	v_mfma_f32_16x16x32_bf16 v[12:15], v[158:161], v[214:217], v[12:15]
	v_mfma_f32_16x16x32_bf16 v[12:15], v[162:165], v[218:221], v[12:15]
	v_mfma_f32_16x16x32_bf16 v[56:59], v[166:169], v[190:193], v[56:59]
	v_mfma_f32_16x16x32_bf16 v[56:59], v[170:173], v[194:197], v[56:59]
	v_mfma_f32_16x16x32_bf16 v[52:55], v[174:177], v[190:193], v[52:55]
	v_mfma_f32_16x16x32_bf16 v[52:55], v[186:189], v[194:197], v[52:55]
	v_mfma_f32_16x16x32_bf16 v[40:43], v[166:169], v[198:201], v[40:43]
	v_mfma_f32_16x16x32_bf16 v[40:43], v[170:173], v[202:205], v[40:43]
	v_mfma_f32_16x16x32_bf16 v[36:39], v[174:177], v[198:201], v[36:39]
	v_mfma_f32_16x16x32_bf16 v[36:39], v[186:189], v[202:205], v[36:39]
	v_mfma_f32_16x16x32_bf16 v[24:27], v[166:169], v[206:209], v[24:27]
	v_mfma_f32_16x16x32_bf16 v[24:27], v[170:173], v[210:213], v[24:27]
	v_mfma_f32_16x16x32_bf16 v[20:23], v[174:177], v[206:209], v[20:23]
	v_mfma_f32_16x16x32_bf16 v[20:23], v[186:189], v[210:213], v[20:23]
	v_mfma_f32_16x16x32_bf16 v[8:11], v[166:169], v[214:217], v[8:11]
	v_mfma_f32_16x16x32_bf16 v[8:11], v[170:173], v[218:221], v[8:11]
	v_mfma_f32_16x16x32_bf16 v[4:7], v[174:177], v[214:217], v[4:7]
	v_mfma_f32_16x16x32_bf16 v[4:7], v[186:189], v[218:221], v[4:7]
	s_barrier
	s_add_i32 s20, s20, 2
	s_add_u32 s10, s10, 0x100
	s_addc_u32 s11, s11, 0
	s_add_u32 s0, s0, 0x100
	s_addc_u32 s1, s1, 0
	s_cmp_gt_u32 s20, 61
	s_cbranch_scc0 .LBB0_1226
	s_and_b64 vcc, exec, s[48:49]
	s_cbranch_vccz .LBB0_1229
	s_barrier
